# mLSTM normaliser row sums (128 rows x 128 bf16) moved from a 2-wave serial VALU loop to 4 bf16 MFMAs per wave with an all-ones A operand (f32 accumulate)
# speedup vs baseline: 1.0060x; 1.0060x over previous
.LBB0_663:
	ds_read_b32 v182, v140
	s_waitcnt vmcnt(3)
	v_and_b32_e32 v199, 0xffff0000, v78
	v_lshlrev_b32_e32 v198, 16, v78
	s_waitcnt vmcnt(2)
	v_and_b32_e32 v231, 0xffff0000, v74
	v_and_b32_e32 v230, 0xffff0000, v80
	s_waitcnt lgkmcnt(0)
	v_sub_f32_e32 v82, v181, v182
	v_mul_f32_e32 v183, 0x3fb8aa3b, v82
	ds_read_b128 v[82:85], v152
	ds_read_b128 v[86:89], v152 offset:1088
	ds_read_b128 v[90:93], v152 offset:64
	ds_read_b128 v[94:97], v152 offset:1152
	v_readlane_b32 s16, v254, 25
	s_waitcnt lgkmcnt(3)
	v_mfma_f32_16x16x32_bf16 v[82:85], v[82:85], v[78:81], 0
	v_readlane_b32 s17, v254, 26
	v_lshlrev_b64 v[132:133], 10, v[132:133]
	s_mov_b32 s0, 0
	s_waitcnt lgkmcnt(2)
	v_mfma_f32_16x16x32_bf16 v[86:89], v[86:89], v[78:81], 0
	s_waitcnt lgkmcnt(1)
	v_mfma_f32_16x16x32_bf16 v[82:85], v[90:93], v[74:77], v[82:85]
	s_waitcnt lgkmcnt(0)
	v_mfma_f32_16x16x32_bf16 v[86:89], v[94:97], v[74:77], v[86:89]
	ds_read_b128 v[90:93], v152 offset:128
	ds_read_b128 v[94:97], v152 offset:1216
	s_waitcnt vmcnt(1) lgkmcnt(1)
	v_mfma_f32_16x16x32_bf16 v[82:85], v[90:93], v[70:73], v[82:85]
	s_waitcnt lgkmcnt(0)
	v_mfma_f32_16x16x32_bf16 v[86:89], v[94:97], v[70:73], v[86:89]
	ds_read_b128 v[90:93], v152 offset:192
	ds_read_b128 v[94:97], v152 offset:1280
	s_waitcnt vmcnt(0) lgkmcnt(1)
	v_mfma_f32_16x16x32_bf16 v[82:85], v[90:93], v[66:69], v[82:85]
	s_waitcnt lgkmcnt(0)
	v_mfma_f32_16x16x32_bf16 v[86:89], v[94:97], v[66:69], v[86:89]
	ds_read_b128 v[90:93], v142
	ds_read_b128 v[94:97], v142 offset:16
	s_waitcnt lgkmcnt(1)
	v_sub_f32_e32 v90, v90, v182
	v_sub_f32_e32 v91, v91, v182
	v_mul_f32_e32 v90, 0x3fb8aa3b, v90
	v_mul_f32_e32 v91, 0x3fb8aa3b, v91
	v_exp_f32_e32 v90, v90
	v_exp_f32_e32 v91, v91
	v_mul_f32_e32 v82, v82, v90
	v_mul_f32_e32 v83, v83, v91
	v_cndmask_b32_e64 v90, v82, 0, s[24:25]
	s_waitcnt lgkmcnt(0)
	v_sub_f32_e32 v82, v94, v182
	v_cndmask_b32_e64 v91, 0, v83, s[26:27]
	v_sub_f32_e32 v83, v95, v182
	v_mul_f32_e32 v82, 0x3fb8aa3b, v82
	v_mul_f32_e32 v83, 0x3fb8aa3b, v83
	v_exp_f32_e32 v82, v82
	v_exp_f32_e32 v83, v83
	s_nop 0
	v_pk_mul_f32 v[82:83], v[86:87], v[82:83]
	s_nop 0
	v_cndmask_b32_e64 v95, v83, 0, s[28:29]
	v_sub_f32_e32 v83, v96, v182
	v_mul_f32_e32 v83, 0x3fb8aa3b, v83
	v_cndmask_b32_e64 v98, v82, 0, s[30:31]
	v_sub_f32_e32 v82, v92, v182
	v_exp_f32_e32 v86, v83
	v_sub_f32_e32 v83, v93, v182
	v_mul_f32_e32 v82, 0x3fb8aa3b, v82
	v_mul_f32_e32 v83, 0x3fb8aa3b, v83
	v_exp_f32_e32 v82, v82
	v_exp_f32_e32 v83, v83
	s_nop 0
	v_pk_mul_f32 v[82:83], v[84:85], v[82:83]
	s_nop 0
	v_cndmask_b32_e64 v85, v82, 0, s[36:37]
	v_sub_f32_e32 v82, v97, v182
	v_mul_f32_e32 v82, 0x3fb8aa3b, v82
	v_exp_f32_e32 v87, v82
	v_cndmask_b32_e64 v84, v83, 0, s[34:35]
	v_pk_mul_f32 v[82:83], v[88:89], v[86:87]
	s_nop 0
	v_cndmask_b32_e64 v87, v82, 0, s[40:41]
	v_add_f32_e32 v82, 0, v90
	v_add_f32_e32 v82, v91, v82
	v_add_f32_e32 v82, v85, v82
	v_add_f32_e32 v82, v84, v82
	v_add_f32_e32 v82, v98, v82
	v_add_f32_e32 v82, v95, v82
	v_cndmask_b32_e64 v86, v83, 0, s[38:39]
	v_add_f32_e32 v82, v87, v82
	v_add_f32_e32 v94, v86, v82
	v_cvt_pk_bf16_f32 v82, v90, v91
	v_cvt_pk_bf16_f32 v83, v85, v84
	v_cvt_pk_bf16_f32 v85, v87, v86
	ds_read_b128 v[86:89], v152 offset:8704
	ds_read_b128 v[90:93], v152 offset:9792
	v_cvt_pk_bf16_f32 v84, v98, v95
	ds_read_b128 v[96:99], v152 offset:8768
	ds_read_b128 v[184:187], v152 offset:9856
	s_waitcnt lgkmcnt(3)
	v_mfma_f32_16x16x32_bf16 v[86:89], v[86:89], v[78:81], 0
	s_waitcnt lgkmcnt(2)
	v_mfma_f32_16x16x32_bf16 v[90:93], v[90:93], v[78:81], 0
	s_waitcnt lgkmcnt(1)
	v_mfma_f32_16x16x32_bf16 v[86:89], v[96:99], v[74:77], v[86:89]
	s_waitcnt lgkmcnt(0)
	v_mfma_f32_16x16x32_bf16 v[90:93], v[184:187], v[74:77], v[90:93]
	ds_read_b128 v[96:99], v152 offset:8832
	ds_read_b128 v[184:187], v152 offset:9920
	s_waitcnt lgkmcnt(1)
	v_mfma_f32_16x16x32_bf16 v[86:89], v[96:99], v[70:73], v[86:89]
	s_waitcnt lgkmcnt(0)
	v_mfma_f32_16x16x32_bf16 v[96:99], v[184:187], v[70:73], v[90:93]
	s_nop 2
	ds_read_b128 v[90:93], v152 offset:8896
	ds_read_b128 v[184:187], v152 offset:9984
	s_waitcnt lgkmcnt(1)
	v_mfma_f32_16x16x32_bf16 v[90:93], v[90:93], v[66:69], v[86:89]
	s_waitcnt lgkmcnt(0)
	v_mfma_f32_16x16x32_bf16 v[86:89], v[184:187], v[66:69], v[96:99]
	s_nop 2
	ds_read_b128 v[96:99], v142 offset:128
	ds_read_b128 v[184:187], v142 offset:144
	s_waitcnt lgkmcnt(1)
	v_sub_f32_e32 v95, v96, v182
	v_mul_f32_e32 v95, 0x3fb8aa3b, v95
	v_exp_f32_e32 v96, v95
	s_waitcnt lgkmcnt(0)
	v_sub_f32_e32 v95, v184, v182
	v_mul_f32_e32 v95, 0x3fb8aa3b, v95
	v_exp_f32_e32 v100, v95
	v_sub_f32_e32 v95, v97, v182
	v_mul_f32_e32 v95, 0x3fb8aa3b, v95
	v_exp_f32_e32 v97, v95
	s_nop 0
	v_pk_mul_f32 v[90:91], v[90:91], v[96:97]
	s_nop 0
	v_cndmask_b32_e64 v96, v90, 0, s[44:45]
	v_sub_f32_e32 v90, v185, v182
	v_mul_f32_e32 v90, 0x3fb8aa3b, v90
	v_exp_f32_e32 v101, v90
	v_cndmask_b32_e64 v95, v91, 0, s[42:43]
	v_pk_mul_f32 v[86:87], v[86:87], v[100:101]
	s_nop 0
	v_cndmask_b32_e64 v97, v87, 0, s[46:47]
	v_sub_f32_e32 v87, v186, v182
	v_mul_f32_e32 v87, 0x3fb8aa3b, v87
	v_cndmask_b32_e64 v100, v86, 0, s[48:49]
	v_sub_f32_e32 v86, v98, v182
	v_exp_f32_e32 v90, v87
	v_sub_f32_e32 v87, v99, v182
	v_mul_f32_e32 v86, 0x3fb8aa3b, v86
	v_mul_f32_e32 v87, 0x3fb8aa3b, v87
	v_exp_f32_e32 v86, v86
	v_exp_f32_e32 v87, v87
	s_nop 0
	v_pk_mul_f32 v[86:87], v[92:93], v[86:87]
	s_nop 0
	v_cndmask_b32_e64 v93, v86, 0, s[52:53]
	v_sub_f32_e32 v86, v187, v182
	v_mul_f32_e32 v86, 0x3fb8aa3b, v86
	v_exp_f32_e32 v91, v86
	v_cndmask_b32_e64 v92, v87, 0, s[50:51]
	v_pk_mul_f32 v[86:87], v[88:89], v[90:91]
	s_nop 0
	v_cndmask_b32_e64 v90, v86, 0, s[56:57]
	v_add_f32_e32 v86, v94, v96
	v_add_f32_e32 v86, v95, v86
	v_add_f32_e32 v86, v93, v86
	v_add_f32_e32 v86, v92, v86
	v_add_f32_e32 v86, v100, v86
	v_add_f32_e32 v86, v97, v86
	v_cndmask_b32_e64 v89, v87, 0, s[54:55]
	v_add_f32_e32 v86, v90, v86
	v_add_f32_e32 v98, v89, v86
	v_cvt_pk_bf16_f32 v86, v96, v95
	v_cvt_pk_bf16_f32 v87, v93, v92
	v_cvt_pk_bf16_f32 v88, v100, v97
	v_cvt_pk_bf16_f32 v89, v90, v89
	ds_read_b128 v[90:93], v152 offset:17408
	ds_read_b128 v[94:97], v152 offset:18496
	ds_read_b128 v[184:187], v152 offset:17472
	ds_read_b128 v[188:191], v152 offset:18560
	s_waitcnt lgkmcnt(3)
	v_mfma_f32_16x16x32_bf16 v[90:93], v[90:93], v[78:81], 0
	s_waitcnt lgkmcnt(2)
	v_mfma_f32_16x16x32_bf16 v[94:97], v[94:97], v[78:81], 0
	s_waitcnt lgkmcnt(1)
	v_mfma_f32_16x16x32_bf16 v[90:93], v[184:187], v[74:77], v[90:93]
	s_waitcnt lgkmcnt(0)
	v_mfma_f32_16x16x32_bf16 v[94:97], v[188:191], v[74:77], v[94:97]
	ds_read_b128 v[184:187], v152 offset:17536
	ds_read_b128 v[188:191], v152 offset:18624
	s_waitcnt lgkmcnt(1)
	v_mfma_f32_16x16x32_bf16 v[90:93], v[184:187], v[70:73], v[90:93]
	s_waitcnt lgkmcnt(0)
	v_mfma_f32_16x16x32_bf16 v[184:187], v[188:191], v[70:73], v[94:97]
	s_nop 2
	ds_read_b128 v[94:97], v152 offset:17600
	ds_read_b128 v[188:191], v152 offset:18688
	s_waitcnt lgkmcnt(1)
	v_mfma_f32_16x16x32_bf16 v[94:97], v[94:97], v[66:69], v[90:93]
	s_waitcnt lgkmcnt(0)
	v_mfma_f32_16x16x32_bf16 v[90:93], v[188:191], v[66:69], v[184:187]
	s_nop 2
	ds_read_b128 v[184:187], v142 offset:256
	ds_read_b128 v[188:191], v142 offset:272
	s_waitcnt lgkmcnt(1)
	v_sub_f32_e32 v99, v184, v182
	v_mul_f32_e32 v99, 0x3fb8aa3b, v99
	v_exp_f32_e32 v100, v99
	s_waitcnt lgkmcnt(0)
	v_sub_f32_e32 v99, v188, v182
	v_mul_f32_e32 v99, 0x3fb8aa3b, v99
	v_exp_f32_e32 v184, v99
	v_sub_f32_e32 v99, v185, v182
	v_mul_f32_e32 v99, 0x3fb8aa3b, v99
	v_exp_f32_e32 v101, v99
	s_nop 0
	v_pk_mul_f32 v[94:95], v[94:95], v[100:101]
	s_nop 0
	v_cndmask_b32_e64 v100, v94, 0, s[60:61]
	v_sub_f32_e32 v94, v189, v182
	v_mul_f32_e32 v94, 0x3fb8aa3b, v94
	v_exp_f32_e32 v185, v94
	v_cndmask_b32_e64 v99, v95, 0, s[58:59]
	v_pk_mul_f32 v[90:91], v[90:91], v[184:185]
	s_nop 0
	v_cndmask_b32_e64 v101, v91, 0, s[62:63]
	v_sub_f32_e32 v91, v190, v182
	v_mul_f32_e32 v91, 0x3fb8aa3b, v91
	v_cndmask_b32_e64 v172, v90, 0, s[64:65]
	v_sub_f32_e32 v90, v186, v182
	v_exp_f32_e32 v94, v91
	v_sub_f32_e32 v91, v187, v182
	v_mul_f32_e32 v90, 0x3fb8aa3b, v90
	v_mul_f32_e32 v91, 0x3fb8aa3b, v91
	v_exp_f32_e32 v90, v90
	v_exp_f32_e32 v91, v91
	s_nop 0
	v_pk_mul_f32 v[90:91], v[96:97], v[90:91]
	s_nop 0
	v_cndmask_b32_e64 v97, v90, 0, s[68:69]
	v_sub_f32_e32 v90, v191, v182
	v_mul_f32_e32 v90, 0x3fb8aa3b, v90
	v_exp_f32_e32 v95, v90
	v_cndmask_b32_e64 v96, v91, 0, s[66:67]
	v_pk_mul_f32 v[90:91], v[92:93], v[94:95]
	s_nop 0
	v_cndmask_b32_e64 v94, v90, 0, s[72:73]
	v_add_f32_e32 v90, v98, v100
	v_add_f32_e32 v90, v99, v90
	v_add_f32_e32 v90, v97, v90
	v_add_f32_e32 v90, v96, v90
	v_add_f32_e32 v90, v172, v90
	v_add_f32_e32 v90, v101, v90
	v_cndmask_b32_e64 v93, v91, 0, s[70:71]
	v_add_f32_e32 v90, v94, v90
	v_add_f32_e32 v184, v93, v90
	v_cvt_pk_bf16_f32 v90, v100, v99
	v_cvt_pk_bf16_f32 v91, v97, v96
	v_cvt_pk_bf16_f32 v92, v172, v101
	v_cvt_pk_bf16_f32 v93, v94, v93
	ds_read_b128 v[94:97], v152 offset:26112
	ds_read_b128 v[98:101], v152 offset:27200
	ds_read_b128 v[186:189], v152 offset:26176
	ds_read_b128 v[190:193], v152 offset:27264
	s_waitcnt lgkmcnt(3)
	v_mfma_f32_16x16x32_bf16 v[94:97], v[94:97], v[78:81], 0
	s_waitcnt lgkmcnt(2)
	v_mfma_f32_16x16x32_bf16 v[98:101], v[98:101], v[78:81], 0
	s_waitcnt lgkmcnt(1)
	v_mfma_f32_16x16x32_bf16 v[94:97], v[186:189], v[74:77], v[94:97]
	s_waitcnt lgkmcnt(0)
	v_mfma_f32_16x16x32_bf16 v[98:101], v[190:193], v[74:77], v[98:101]
	ds_read_b128 v[186:189], v152 offset:26240
	ds_read_b128 v[190:193], v152 offset:27328
	s_waitcnt lgkmcnt(1)
	v_mfma_f32_16x16x32_bf16 v[94:97], v[186:189], v[70:73], v[94:97]
	s_waitcnt lgkmcnt(0)
	v_mfma_f32_16x16x32_bf16 v[186:189], v[190:193], v[70:73], v[98:101]
	s_nop 2
	ds_read_b128 v[98:101], v152 offset:26304
	ds_read_b128 v[190:193], v152 offset:27392
	s_waitcnt lgkmcnt(1)
	v_mfma_f32_16x16x32_bf16 v[98:101], v[98:101], v[66:69], v[94:97]
	s_waitcnt lgkmcnt(0)
	v_mfma_f32_16x16x32_bf16 v[94:97], v[190:193], v[66:69], v[186:189]
	s_nop 2
	ds_read_b128 v[186:189], v142 offset:384
	ds_read_b128 v[190:193], v142 offset:400
	s_waitcnt lgkmcnt(1)
	v_sub_f32_e32 v172, v186, v182
	v_mul_f32_e32 v172, 0x3fb8aa3b, v172
	v_exp_f32_e32 v186, v172
	s_waitcnt lgkmcnt(0)
	v_sub_f32_e32 v172, v190, v182
	v_mul_f32_e32 v172, 0x3fb8aa3b, v172
	v_exp_f32_e32 v190, v172
	v_sub_f32_e32 v172, v187, v182
	v_mul_f32_e32 v172, 0x3fb8aa3b, v172
	v_exp_f32_e32 v187, v172
	s_nop 0
	v_pk_mul_f32 v[98:99], v[98:99], v[186:187]
	s_nop 0
	v_cndmask_b32_e64 v173, v98, 0, s[76:77]
	v_sub_f32_e32 v98, v191, v182
	v_mul_f32_e32 v98, 0x3fb8aa3b, v98
	v_exp_f32_e32 v191, v98
	v_cndmask_b32_e64 v172, v99, 0, s[74:75]
	v_pk_mul_f32 v[94:95], v[94:95], v[190:191]
	s_nop 0
	v_cndmask_b32_e64 v190, v95, 0, s[78:79]
	v_sub_f32_e32 v95, v192, v182
	v_mul_f32_e32 v95, 0x3fb8aa3b, v95
	v_cndmask_b32_e64 v194, v94, 0, s[80:81]
	v_sub_f32_e32 v94, v188, v182
	v_exp_f32_e32 v98, v95
	v_sub_f32_e32 v95, v189, v182
	v_mul_f32_e32 v94, 0x3fb8aa3b, v94
	v_mul_f32_e32 v95, 0x3fb8aa3b, v95
	v_exp_f32_e32 v94, v94
	v_exp_f32_e32 v95, v95
	s_nop 0
	v_pk_mul_f32 v[94:95], v[100:101], v[94:95]
	s_nop 0
	v_cndmask_b32_e64 v101, v94, 0, s[84:85]
	v_sub_f32_e32 v94, v193, v182
	v_mul_f32_e32 v94, 0x3fb8aa3b, v94
	v_exp_f32_e32 v99, v94
	v_cndmask_b32_e64 v100, v95, 0, s[82:83]
	v_pk_mul_f32 v[94:95], v[96:97], v[98:99]
	s_nop 0
	v_cndmask_b32_e64 v192, v94, 0, s[88:89]
	v_add_f32_e32 v94, v184, v173
	v_add_f32_e32 v94, v172, v94
	v_add_f32_e32 v94, v101, v94
	v_add_u32_e32 v98, 0, v141
	v_add_f32_e32 v196, v100, v94
	v_cvt_pk_bf16_f32 v94, v173, v172
	v_add_u32_e32 v172, 0x22600, v98
	v_cndmask_b32_e64 v188, v95, 0, s[86:87]
	v_cvt_pk_bf16_f32 v95, v101, v100
	ds_read_b128 v[98:101], v172
	ds_read_b128 v[184:187], v172 offset:16
	v_cvt_pk_bf16_f32 v97, v192, v188
	v_cvt_pk_bf16_f32 v96, v194, v190
	s_waitcnt lgkmcnt(1)
	v_pk_mul_f32 v[98:99], v[98:99], v[198:199]
	v_and_b32_e32 v199, 0xffff0000, v79
	v_lshlrev_b32_e32 v198, 16, v79
	v_pk_mul_f32 v[100:101], v[100:101], v[198:199]
	v_add_f32_e32 v98, v98, v99
	v_add_f32_e32 v98, v100, v98
	v_add_f32_e32 v98, v101, v98
	v_add_f32_e32 v173, 0, v98
	ds_read_b128 v[98:101], v172 offset:128
	v_lshlrev_b32_e32 v199, 16, v74
	v_lshlrev_b32_e32 v198, 16, v80
	s_waitcnt lgkmcnt(1)
	v_mov_b32_e32 v200, v184
	v_lshlrev_b32_e32 v184, 16, v81
	s_waitcnt lgkmcnt(0)
	v_mov_b32_e32 v201, v98
	v_mov_b32_e32 v98, v185
	v_pk_mul_f32 v[98:99], v[98:99], v[230:231]
	v_lshlrev_b32_e32 v185, 16, v75
	v_pk_fma_f32 v[98:99], v[200:201], v[198:199], v[98:99]
	v_mov_b32_e32 v198, v186
	v_mov_b32_e32 v199, v100
	v_pk_fma_f32 v[98:99], v[198:199], v[184:185], v[98:99]
	v_and_b32_e32 v185, 0xffff0000, v75
	v_and_b32_e32 v184, 0xffff0000, v81
	v_mov_b32_e32 v100, v187
	v_pk_fma_f32 v[98:99], v[100:101], v[184:185], v[98:99]
	v_and_b32_e32 v231, 0xffff0000, v70
	v_add_f32_e32 v98, v173, v98
	v_add_f32_e32 v173, v98, v99
	ds_read_b128 v[98:101], v172 offset:144
	ds_read_b128 v[184:187], v172 offset:256
	v_and_b32_e32 v230, 0xffff0000, v76
	v_lshlrev_b32_e32 v199, 16, v70
	v_lshlrev_b32_e32 v198, 16, v76
	s_waitcnt lgkmcnt(1)
	v_mov_b32_e32 v200, v98
	s_waitcnt lgkmcnt(0)
	v_mov_b32_e32 v201, v184
	v_mov_b32_e32 v184, v99
	v_pk_mul_f32 v[98:99], v[184:185], v[230:231]
	v_lshlrev_b32_e32 v185, 16, v71
	v_pk_fma_f32 v[98:99], v[200:201], v[198:199], v[98:99]
	v_lshlrev_b32_e32 v184, 16, v77
	v_mov_b32_e32 v198, v100
	v_mov_b32_e32 v199, v186
	v_pk_fma_f32 v[98:99], v[198:199], v[184:185], v[98:99]
	v_and_b32_e32 v185, 0xffff0000, v71
	v_and_b32_e32 v184, 0xffff0000, v77
	v_mov_b32_e32 v186, v101
	v_pk_fma_f32 v[98:99], v[186:187], v[184:185], v[98:99]
	v_and_b32_e32 v231, 0xffff0000, v66
	v_add_f32_e32 v98, v173, v98
	v_add_f32_e32 v173, v98, v99
	ds_read_b128 v[98:101], v172 offset:272
	ds_read_b128 v[184:187], v172 offset:384
	v_and_b32_e32 v230, 0xffff0000, v72
	v_lshlrev_b32_e32 v199, 16, v66
	v_lshlrev_b32_e32 v198, 16, v72
	s_waitcnt lgkmcnt(1)
	v_mov_b32_e32 v200, v98
	s_waitcnt lgkmcnt(0)
	v_mov_b32_e32 v201, v184
	v_mov_b32_e32 v184, v99
	v_pk_mul_f32 v[98:99], v[184:185], v[230:231]
	v_lshlrev_b32_e32 v185, 16, v67
	v_pk_fma_f32 v[98:99], v[200:201], v[198:199], v[98:99]
	v_lshlrev_b32_e32 v184, 16, v73
	v_mov_b32_e32 v198, v100
	v_mov_b32_e32 v199, v186
	v_pk_fma_f32 v[98:99], v[198:199], v[184:185], v[98:99]
	v_and_b32_e32 v185, 0xffff0000, v67
	v_and_b32_e32 v184, 0xffff0000, v73
	v_mov_b32_e32 v186, v101
	v_pk_fma_f32 v[98:99], v[186:187], v[184:185], v[98:99]
	s_load_dwordx2 s[16:17], s[16:17], 0x118
	v_add_f32_e32 v98, v173, v98
	v_add_f32_e32 v189, v98, v99
	ds_read_b128 v[98:101], v172 offset:400
	v_lshlrev_b32_e32 v172, 16, v68
	s_waitcnt lgkmcnt(0)
	v_lshl_add_u64 v[134:135], s[16:17], 0, v[134:135]
	s_mov_b64 s[16:17], 0x2134200
	v_lshl_add_u64 v[134:135], v[134:135], 0, s[16:17]
	v_mul_f32_e32 v195, v98, v172
	v_and_b32_e32 v98, 0xffff0000, v68
	v_mul_f32_e32 v197, v99, v98
	v_lshlrev_b32_e32 v98, 16, v69
	v_mul_f32_e32 v191, v100, v98
	v_and_b32_e32 v98, 0xffff0000, v69
	v_mul_f32_e32 v193, v101, v98
	v_pk_add_f32 v[100:101], v[194:195], v[196:197]
	ds_read_b32 v99, v145
	v_pk_add_f32 v[100:101], v[190:191], v[100:101]
	v_exp_f32_e32 v98, v183
	v_pk_add_f32 v[100:101], v[192:193], v[100:101]
	v_readlane_b32 s16, v254, 60
	v_pk_add_f32 v[100:101], v[188:189], v[100:101]
	ds_bpermute_b32 v184, v143, v100
	ds_bpermute_b32 v185, v143, v101
	ds_read_b128 v[186:189], v169 offset:64
	s_waitcnt lgkmcnt(3)
	v_add_f32_e32 v99, v182, v99
	v_mul_f32_e32 v99, 0xbfb8aa3b, v99
	v_exp_f32_e32 v99, v99
	s_waitcnt lgkmcnt(1)
	v_pk_add_f32 v[100:101], v[100:101], v[184:185]
	ds_bpermute_b32 v184, v144, v100
	ds_bpermute_b32 v185, v144, v101
	v_readlane_b32 s17, v254, 61
	s_waitcnt lgkmcnt(0)
	v_pk_add_f32 v[100:101], v[100:101], v[184:185]
	ds_read_b128 v[182:185], v169
	s_waitcnt lgkmcnt(0)
	v_mfma_f32_16x16x32_bf16 v[182:185], v[182:185], v[78:81], 0
	v_fmac_f32_e32 v100, v98, v101
	v_max_f32_e64 v99, |v100|, v99
	v_div_scale_f32 v100, s[90:91], v99, v99, 1.0
	v_mfma_f32_16x16x32_bf16 v[182:185], v[186:189], v[74:77], v[182:185]
	ds_read_b128 v[186:189], v169 offset:128
	v_rcp_f32_e32 v101, v100
	v_lshl_add_u64 v[132:133], s[16:17], 0, v[132:133]
	s_waitcnt lgkmcnt(0)
	v_mfma_f32_16x16x32_bf16 v[182:185], v[186:189], v[70:73], v[182:185]
	ds_read_b128 v[186:189], v169 offset:192
	v_fma_f32 v172, -v100, v101, 1.0
	v_fmac_f32_e32 v101, v172, v101
	s_waitcnt lgkmcnt(0)
	v_mfma_f32_16x16x32_bf16 v[182:185], v[186:189], v[66:69], v[182:185]
	ds_read_b128 v[186:189], v176
	v_div_scale_f32 v172, vcc, 1.0, v99, 1.0
	s_nop 5
	v_pk_mul_f32 v[184:185], v[98:99], v[184:185] op_sel_hi:[0,1]
	v_pk_mul_f32 v[182:183], v[98:99], v[182:183] op_sel_hi:[0,1]
	v_mul_f32_e32 v173, v172, v101
	v_fma_f32 v174, -v100, v173, v172
	s_waitcnt lgkmcnt(0)
	v_mfma_f32_16x16x32_bf16 v[182:185], v[186:189], v[82:85], v[182:185]
	ds_read_b128 v[186:189], v176 offset:64
	v_fmac_f32_e32 v173, v174, v101
	v_fma_f32 v100, -v100, v173, v172
	s_waitcnt lgkmcnt(0)
	v_mfma_f32_16x16x32_bf16 v[182:185], v[186:189], v[86:89], v[182:185]
	ds_read_b128 v[186:189], v176 offset:128
	v_div_fmas_f32 v100, v100, v101, v173
	v_readlane_b32 s90, v254, 19
	s_waitcnt lgkmcnt(0)
	v_mfma_f32_16x16x32_bf16 v[182:185], v[186:189], v[90:93], v[182:185]
	ds_read_b128 v[186:189], v176 offset:192
	v_div_fixup_f32 v100, v100, v99, 1.0
	v_cndmask_b32_e64 v133, v133, v135, s[6:7]
	s_waitcnt lgkmcnt(0)
	v_mfma_f32_16x16x32_bf16 v[182:185], v[186:189], v[94:97], v[182:185]
	v_cndmask_b32_e64 v132, v132, v134, s[6:7]
	v_readlane_b32 s91, v254, 20
	ds_read_b128 v[186:189], v169 offset:4416
	s_nop 4
	v_pk_mul_f32 v[134:135], v[100:101], v[184:185] op_sel_hi:[0,1]
	v_lshl_add_u64 v[132:133], v[132:133], 0, s[90:91]
	v_pk_mul_f32 v[182:183], v[100:101], v[182:183] op_sel_hi:[0,1]
	v_lshl_add_u64 v[132:133], v[132:133], 0, v[0:1]
	v_cvt_pk_bf16_f32 v182, v182, v183
	v_cvt_pk_bf16_f32 v183, v134, v135
	global_store_dwordx2 v[132:133], v[182:183], off
	ds_read_b128 v[182:185], v169 offset:4352
	s_waitcnt lgkmcnt(0)
	v_mfma_f32_16x16x32_bf16 v[182:185], v[182:185], v[78:81], 0
	v_mfma_f32_16x16x32_bf16 v[182:185], v[186:189], v[74:77], v[182:185]
	ds_read_b128 v[186:189], v169 offset:4480
	s_waitcnt lgkmcnt(0)
	v_mfma_f32_16x16x32_bf16 v[182:185], v[186:189], v[70:73], v[182:185]
	ds_read_b128 v[186:189], v169 offset:4544
	s_waitcnt lgkmcnt(0)
	v_mfma_f32_16x16x32_bf16 v[182:185], v[186:189], v[66:69], v[182:185]
	ds_read_b128 v[186:189], v176 offset:4352
	s_nop 6
	v_pk_mul_f32 v[184:185], v[98:99], v[184:185] op_sel_hi:[0,1]
	v_pk_mul_f32 v[182:183], v[98:99], v[182:183] op_sel_hi:[0,1]
	s_waitcnt lgkmcnt(0)
	s_nop 0
	v_mfma_f32_16x16x32_bf16 v[182:185], v[186:189], v[82:85], v[182:185]
	ds_read_b128 v[186:189], v176 offset:4416
	s_waitcnt lgkmcnt(0)
	v_mfma_f32_16x16x32_bf16 v[182:185], v[186:189], v[86:89], v[182:185]
	ds_read_b128 v[186:189], v176 offset:4480
	s_waitcnt lgkmcnt(0)
	v_mfma_f32_16x16x32_bf16 v[182:185], v[186:189], v[90:93], v[182:185]
	ds_read_b128 v[186:189], v176 offset:4544
	s_waitcnt lgkmcnt(0)
	v_mfma_f32_16x16x32_bf16 v[182:185], v[186:189], v[94:97], v[182:185]
	ds_read_b128 v[186:189], v169 offset:8768
	s_nop 6
	v_pk_mul_f32 v[134:135], v[100:101], v[184:185] op_sel_hi:[0,1]
	v_pk_mul_f32 v[182:183], v[100:101], v[182:183] op_sel_hi:[0,1]
	v_cvt_pk_bf16_f32 v182, v182, v183
	v_cvt_pk_bf16_f32 v183, v134, v135
	global_store_dwordx2 v[132:133], v[182:183], off offset:32
	ds_read_b128 v[182:185], v169 offset:8704
	s_waitcnt lgkmcnt(0)
	v_mfma_f32_16x16x32_bf16 v[182:185], v[182:185], v[78:81], 0
	v_mfma_f32_16x16x32_bf16 v[182:185], v[186:189], v[74:77], v[182:185]
	ds_read_b128 v[186:189], v169 offset:8832
	s_waitcnt lgkmcnt(0)
	v_mfma_f32_16x16x32_bf16 v[182:185], v[186:189], v[70:73], v[182:185]
	ds_read_b128 v[186:189], v169 offset:8896
	s_waitcnt lgkmcnt(0)
	v_mfma_f32_16x16x32_bf16 v[182:185], v[186:189], v[66:69], v[182:185]
	ds_read_b128 v[186:189], v176 offset:8704
	s_nop 6
	v_pk_mul_f32 v[184:185], v[98:99], v[184:185] op_sel_hi:[0,1]
	v_pk_mul_f32 v[182:183], v[98:99], v[182:183] op_sel_hi:[0,1]
	s_waitcnt lgkmcnt(0)
	s_nop 0
	v_mfma_f32_16x16x32_bf16 v[182:185], v[186:189], v[82:85], v[182:185]
	ds_read_b128 v[186:189], v176 offset:8768
	s_waitcnt lgkmcnt(0)
	v_mfma_f32_16x16x32_bf16 v[182:185], v[186:189], v[86:89], v[182:185]
	ds_read_b128 v[186:189], v176 offset:8832
	s_waitcnt lgkmcnt(0)
	v_mfma_f32_16x16x32_bf16 v[182:185], v[186:189], v[90:93], v[182:185]
	ds_read_b128 v[186:189], v176 offset:8896
	s_waitcnt lgkmcnt(0)
	v_mfma_f32_16x16x32_bf16 v[182:185], v[186:189], v[94:97], v[182:185]
	ds_read_b128 v[186:189], v169 offset:13120
	s_nop 6
	v_pk_mul_f32 v[134:135], v[100:101], v[184:185] op_sel_hi:[0,1]
	v_pk_mul_f32 v[182:183], v[100:101], v[182:183] op_sel_hi:[0,1]
	v_cvt_pk_bf16_f32 v182, v182, v183
	v_cvt_pk_bf16_f32 v183, v134, v135
	global_store_dwordx2 v[132:133], v[182:183], off offset:64
	ds_read_b128 v[182:185], v169 offset:13056
	s_waitcnt lgkmcnt(0)
	v_mfma_f32_16x16x32_bf16 v[182:185], v[182:185], v[78:81], 0
	v_mfma_f32_16x16x32_bf16 v[182:185], v[186:189], v[74:77], v[182:185]
	ds_read_b128 v[186:189], v169 offset:13184
	s_waitcnt lgkmcnt(0)
	v_mfma_f32_16x16x32_bf16 v[182:185], v[186:189], v[70:73], v[182:185]
	ds_read_b128 v[186:189], v169 offset:13248
	s_waitcnt lgkmcnt(0)
	v_mfma_f32_16x16x32_bf16 v[182:185], v[186:189], v[66:69], v[182:185]
	ds_read_b128 v[186:189], v176 offset:13056
	s_nop 6
	v_pk_mul_f32 v[184:185], v[98:99], v[184:185] op_sel_hi:[0,1]
	v_pk_mul_f32 v[182:183], v[98:99], v[182:183] op_sel_hi:[0,1]
	s_waitcnt lgkmcnt(0)
	s_nop 0
	v_mfma_f32_16x16x32_bf16 v[182:185], v[186:189], v[82:85], v[182:185]
	ds_read_b128 v[186:189], v176 offset:13120
	s_waitcnt lgkmcnt(0)
	v_mfma_f32_16x16x32_bf16 v[182:185], v[186:189], v[86:89], v[182:185]
	ds_read_b128 v[186:189], v176 offset:13184
	s_waitcnt lgkmcnt(0)
	v_mfma_f32_16x16x32_bf16 v[182:185], v[186:189], v[90:93], v[182:185]
	ds_read_b128 v[186:189], v176 offset:13248
	s_waitcnt lgkmcnt(0)
	v_mfma_f32_16x16x32_bf16 v[182:185], v[186:189], v[94:97], v[182:185]
	ds_read_b128 v[186:189], v169 offset:17472
	s_nop 6
	v_pk_mul_f32 v[134:135], v[100:101], v[184:185] op_sel_hi:[0,1]
	v_pk_mul_f32 v[182:183], v[100:101], v[182:183] op_sel_hi:[0,1]
	v_cvt_pk_bf16_f32 v182, v182, v183
	v_cvt_pk_bf16_f32 v183, v134, v135
	global_store_dwordx2 v[132:133], v[182:183], off offset:96
	ds_read_b128 v[182:185], v169 offset:17408
	s_waitcnt lgkmcnt(0)
	v_mfma_f32_16x16x32_bf16 v[182:185], v[182:185], v[78:81], 0
	v_mfma_f32_16x16x32_bf16 v[182:185], v[186:189], v[74:77], v[182:185]
	ds_read_b128 v[186:189], v169 offset:17536
	s_waitcnt lgkmcnt(0)
	v_mfma_f32_16x16x32_bf16 v[182:185], v[186:189], v[70:73], v[182:185]
	ds_read_b128 v[186:189], v169 offset:17600
	s_waitcnt lgkmcnt(0)
	v_mfma_f32_16x16x32_bf16 v[182:185], v[186:189], v[66:69], v[182:185]
	ds_read_b128 v[186:189], v176 offset:17408
	s_nop 6
	v_pk_mul_f32 v[184:185], v[98:99], v[184:185] op_sel_hi:[0,1]
	v_pk_mul_f32 v[182:183], v[98:99], v[182:183] op_sel_hi:[0,1]
	s_waitcnt lgkmcnt(0)
	s_nop 0
	v_mfma_f32_16x16x32_bf16 v[182:185], v[186:189], v[82:85], v[182:185]
	ds_read_b128 v[186:189], v176 offset:17472
	s_waitcnt lgkmcnt(0)
	v_mfma_f32_16x16x32_bf16 v[182:185], v[186:189], v[86:89], v[182:185]
	ds_read_b128 v[186:189], v176 offset:17536
	s_waitcnt lgkmcnt(0)
	v_mfma_f32_16x16x32_bf16 v[182:185], v[186:189], v[90:93], v[182:185]
	ds_read_b128 v[186:189], v176 offset:17600
	s_waitcnt lgkmcnt(0)
	v_mfma_f32_16x16x32_bf16 v[182:185], v[186:189], v[94:97], v[182:185]
	ds_read_b128 v[186:189], v169 offset:21824
	s_nop 6
	v_pk_mul_f32 v[134:135], v[100:101], v[184:185] op_sel_hi:[0,1]
	v_pk_mul_f32 v[182:183], v[100:101], v[182:183] op_sel_hi:[0,1]
	v_cvt_pk_bf16_f32 v182, v182, v183
	v_cvt_pk_bf16_f32 v183, v134, v135
	global_store_dwordx2 v[132:133], v[182:183], off offset:128
	ds_read_b128 v[182:185], v169 offset:21760
	s_waitcnt lgkmcnt(0)
	v_mfma_f32_16x16x32_bf16 v[182:185], v[182:185], v[78:81], 0
	v_mfma_f32_16x16x32_bf16 v[182:185], v[186:189], v[74:77], v[182:185]
	ds_read_b128 v[186:189], v169 offset:21888
	s_waitcnt lgkmcnt(0)
	v_mfma_f32_16x16x32_bf16 v[182:185], v[186:189], v[70:73], v[182:185]
	ds_read_b128 v[186:189], v169 offset:21952
	s_waitcnt lgkmcnt(0)
	v_mfma_f32_16x16x32_bf16 v[182:185], v[186:189], v[66:69], v[182:185]
	ds_read_b128 v[186:189], v176 offset:21760
	s_nop 6
	v_pk_mul_f32 v[184:185], v[98:99], v[184:185] op_sel_hi:[0,1]
	v_pk_mul_f32 v[182:183], v[98:99], v[182:183] op_sel_hi:[0,1]
	s_waitcnt lgkmcnt(0)
	s_nop 0
	v_mfma_f32_16x16x32_bf16 v[182:185], v[186:189], v[82:85], v[182:185]
	ds_read_b128 v[186:189], v176 offset:21824
	s_waitcnt lgkmcnt(0)
	v_mfma_f32_16x16x32_bf16 v[182:185], v[186:189], v[86:89], v[182:185]
	ds_read_b128 v[186:189], v176 offset:21888
	s_waitcnt lgkmcnt(0)
	v_mfma_f32_16x16x32_bf16 v[182:185], v[186:189], v[90:93], v[182:185]
	ds_read_b128 v[186:189], v176 offset:21952
	s_waitcnt lgkmcnt(0)
	v_mfma_f32_16x16x32_bf16 v[182:185], v[186:189], v[94:97], v[182:185]
	ds_read_b128 v[186:189], v169 offset:26176
	s_nop 6
	v_pk_mul_f32 v[134:135], v[100:101], v[184:185] op_sel_hi:[0,1]
	v_pk_mul_f32 v[182:183], v[100:101], v[182:183] op_sel_hi:[0,1]
	v_cvt_pk_bf16_f32 v182, v182, v183
	v_cvt_pk_bf16_f32 v183, v134, v135
	global_store_dwordx2 v[132:133], v[182:183], off offset:160
	ds_read_b128 v[182:185], v169 offset:26112
	s_waitcnt lgkmcnt(0)
	v_mfma_f32_16x16x32_bf16 v[182:185], v[182:185], v[78:81], 0
	v_mfma_f32_16x16x32_bf16 v[182:185], v[186:189], v[74:77], v[182:185]
	ds_read_b128 v[186:189], v169 offset:26240
	s_waitcnt lgkmcnt(0)
	v_mfma_f32_16x16x32_bf16 v[182:185], v[186:189], v[70:73], v[182:185]
	ds_read_b128 v[186:189], v169 offset:26304
	s_waitcnt lgkmcnt(0)
	v_mfma_f32_16x16x32_bf16 v[182:185], v[186:189], v[66:69], v[182:185]
	ds_read_b128 v[186:189], v176 offset:26112
	s_nop 6
	v_pk_mul_f32 v[184:185], v[98:99], v[184:185] op_sel_hi:[0,1]
	v_pk_mul_f32 v[182:183], v[98:99], v[182:183] op_sel_hi:[0,1]
	s_waitcnt lgkmcnt(0)
	s_nop 0
	v_mfma_f32_16x16x32_bf16 v[182:185], v[186:189], v[82:85], v[182:185]
	ds_read_b128 v[186:189], v176 offset:26176
	s_waitcnt lgkmcnt(0)
	v_mfma_f32_16x16x32_bf16 v[182:185], v[186:189], v[86:89], v[182:185]
	ds_read_b128 v[186:189], v176 offset:26240
	s_waitcnt lgkmcnt(0)
	v_mfma_f32_16x16x32_bf16 v[182:185], v[186:189], v[90:93], v[182:185]
	ds_read_b128 v[186:189], v176 offset:26304
	s_waitcnt lgkmcnt(0)
	v_mfma_f32_16x16x32_bf16 v[182:185], v[186:189], v[94:97], v[182:185]
	s_nop 7
	v_pk_mul_f32 v[134:135], v[100:101], v[184:185] op_sel_hi:[0,1]
	v_pk_mul_f32 v[182:183], v[100:101], v[182:183] op_sel_hi:[0,1]
	v_cvt_pk_bf16_f32 v182, v182, v183
	v_cvt_pk_bf16_f32 v183, v134, v135
	global_store_dwordx2 v[132:133], v[182:183], off offset:192
	ds_read_b128 v[182:185], v169 offset:30464
	s_waitcnt lgkmcnt(0)
	v_mfma_f32_16x16x32_bf16 v[78:81], v[182:185], v[78:81], 0
	ds_read_b128 v[182:185], v169 offset:30528
	s_waitcnt lgkmcnt(0)
	v_mfma_f32_16x16x32_bf16 v[74:77], v[182:185], v[74:77], v[78:81]
	s_nop 4
	ds_read_b128 v[78:81], v169 offset:30592
	s_waitcnt lgkmcnt(0)
	v_mfma_f32_16x16x32_bf16 v[70:73], v[78:81], v[70:73], v[74:77]
	s_nop 2
	ds_read_b128 v[74:77], v169 offset:30656
	s_waitcnt lgkmcnt(0)
	v_mfma_f32_16x16x32_bf16 v[66:69], v[74:77], v[66:69], v[70:73]
	s_nop 2
	ds_read_b128 v[70:73], v176 offset:30464
	s_nop 3
	v_pk_mul_f32 v[68:69], v[98:99], v[68:69] op_sel_hi:[0,1]
	v_pk_mul_f32 v[66:67], v[98:99], v[66:67] op_sel_hi:[0,1]
	s_waitcnt lgkmcnt(0)
	s_nop 0
	v_mfma_f32_16x16x32_bf16 v[66:69], v[70:73], v[82:85], v[66:69]
	ds_read_b128 v[70:73], v176 offset:30528
	s_waitcnt lgkmcnt(0)
	v_mfma_f32_16x16x32_bf16 v[66:69], v[70:73], v[86:89], v[66:69]
	ds_read_b128 v[70:73], v176 offset:30592
	s_waitcnt lgkmcnt(0)
	v_mfma_f32_16x16x32_bf16 v[66:69], v[70:73], v[90:93], v[66:69]
	ds_read_b128 v[70:73], v176 offset:30656
	s_waitcnt lgkmcnt(0)
	v_mfma_f32_16x16x32_bf16 v[66:69], v[70:73], v[94:97], v[66:69]
	s_nop 7
	v_pk_mul_f32 v[68:69], v[100:101], v[68:69] op_sel_hi:[0,1]
	v_pk_mul_f32 v[66:67], v[100:101], v[66:67] op_sel_hi:[0,1]
	v_cvt_pk_bf16_f32 v66, v66, v67
	v_cvt_pk_bf16_f32 v67, v68, v69
	global_store_dwordx2 v[132:133], v[66:67], off offset:224
	v_sub_f32_e32 v66, v181, v179
	v_mul_f32_e32 v82, 0x3fb8aa3b, v66
	ds_read_b128 v[78:81], v177
	ds_read_b128 v[74:77], v177 offset:64
	ds_read_b128 v[70:73], v177 offset:128
	ds_read_b128 v[66:69], v177 offset:192
	v_exp_f32_e32 v82, v82
	ds_read_b128 v[84:87], v178 offset:34816
	v_pk_mul_f32 v[48:49], v[48:49], v[82:83] op_sel_hi:[1,0]
	v_pk_mul_f32 v[46:47], v[46:47], v[82:83] op_sel_hi:[1,0]
	v_pk_mul_f32 v[64:65], v[64:65], v[82:83] op_sel_hi:[1,0]
	v_pk_mul_f32 v[62:63], v[62:63], v[82:83] op_sel_hi:[1,0]
	s_waitcnt lgkmcnt(0)
	v_mfma_f32_16x16x32_bf16 v[46:49], v[78:81], v[84:87], v[46:49]
	ds_read_b128 v[84:87], v178 offset:34880
	v_pk_mul_f32 v[60:61], v[60:61], v[82:83] op_sel_hi:[1,0]
	v_pk_mul_f32 v[58:59], v[58:59], v[82:83] op_sel_hi:[1,0]
	s_waitcnt lgkmcnt(0)
	v_mfma_f32_16x16x32_bf16 v[46:49], v[74:77], v[84:87], v[46:49]
	ds_read_b128 v[84:87], v178 offset:34944
	v_pk_mul_f32 v[52:53], v[52:53], v[82:83] op_sel_hi:[1,0]
	v_pk_mul_f32 v[50:51], v[50:51], v[82:83] op_sel_hi:[1,0]
	s_waitcnt lgkmcnt(0)
	v_mfma_f32_16x16x32_bf16 v[46:49], v[70:73], v[84:87], v[46:49]
	ds_read_b128 v[84:87], v178 offset:35008
	v_pk_mul_f32 v[44:45], v[44:45], v[82:83] op_sel_hi:[1,0]
	v_pk_mul_f32 v[42:43], v[42:43], v[82:83] op_sel_hi:[1,0]
	s_waitcnt lgkmcnt(0)
	v_mfma_f32_16x16x32_bf16 v[46:49], v[66:69], v[84:87], v[46:49]
	ds_read_b128 v[84:87], v178 offset:39168
	v_pk_mul_f32 v[40:41], v[40:41], v[82:83] op_sel_hi:[1,0]
	v_pk_mul_f32 v[38:39], v[38:39], v[82:83] op_sel_hi:[1,0]
	s_waitcnt lgkmcnt(0)
	v_mfma_f32_16x16x32_bf16 v[62:65], v[78:81], v[84:87], v[62:65]
	ds_read_b128 v[84:87], v178 offset:39232
	v_pk_mul_f32 v[36:37], v[36:37], v[82:83] op_sel_hi:[1,0]
	v_pk_mul_f32 v[34:35], v[34:35], v[82:83] op_sel_hi:[1,0]
	s_waitcnt lgkmcnt(0)
	v_mfma_f32_16x16x32_bf16 v[62:65], v[74:77], v[84:87], v[62:65]
	ds_read_b128 v[84:87], v178 offset:39296
	v_pk_mul_f32 v[56:57], v[56:57], v[82:83] op_sel_hi:[1,0]
	v_pk_mul_f32 v[54:55], v[54:55], v[82:83] op_sel_hi:[1,0]
	s_waitcnt lgkmcnt(0)
	v_mfma_f32_16x16x32_bf16 v[62:65], v[70:73], v[84:87], v[62:65]
	ds_read_b128 v[84:87], v178 offset:39360
	s_waitcnt lgkmcnt(0)
	v_mfma_f32_16x16x32_bf16 v[62:65], v[66:69], v[84:87], v[62:65]
	ds_read_b128 v[84:87], v178 offset:43520
	s_waitcnt lgkmcnt(0)
	v_mfma_f32_16x16x32_bf16 v[58:61], v[78:81], v[84:87], v[58:61]
	ds_read_b128 v[84:87], v178 offset:43584
	s_waitcnt lgkmcnt(0)
	v_mfma_f32_16x16x32_bf16 v[58:61], v[74:77], v[84:87], v[58:61]
	ds_read_b128 v[84:87], v178 offset:43648
	s_waitcnt lgkmcnt(0)
	v_mfma_f32_16x16x32_bf16 v[58:61], v[70:73], v[84:87], v[58:61]
	ds_read_b128 v[84:87], v178 offset:43712
	s_waitcnt lgkmcnt(0)
	v_mfma_f32_16x16x32_bf16 v[58:61], v[66:69], v[84:87], v[58:61]
	ds_read_b128 v[84:87], v178 offset:47872
	s_waitcnt lgkmcnt(0)
	v_mfma_f32_16x16x32_bf16 v[50:53], v[78:81], v[84:87], v[50:53]
	ds_read_b128 v[84:87], v178 offset:47936
	s_waitcnt lgkmcnt(0)
	v_mfma_f32_16x16x32_bf16 v[50:53], v[74:77], v[84:87], v[50:53]
	ds_read_b128 v[84:87], v178 offset:48000
	s_waitcnt lgkmcnt(0)
	v_mfma_f32_16x16x32_bf16 v[50:53], v[70:73], v[84:87], v[50:53]
	ds_read_b128 v[84:87], v178 offset:48064
	s_waitcnt lgkmcnt(0)
	v_mfma_f32_16x16x32_bf16 v[50:53], v[66:69], v[84:87], v[50:53]
	ds_read_b128 v[84:87], v178 offset:52224
	s_waitcnt lgkmcnt(0)
	v_mfma_f32_16x16x32_bf16 v[42:45], v[78:81], v[84:87], v[42:45]
	ds_read_b128 v[84:87], v178 offset:52288
	s_waitcnt lgkmcnt(0)
	v_mfma_f32_16x16x32_bf16 v[42:45], v[74:77], v[84:87], v[42:45]
	ds_read_b128 v[84:87], v178 offset:52352
	s_waitcnt lgkmcnt(0)
	v_mfma_f32_16x16x32_bf16 v[42:45], v[70:73], v[84:87], v[42:45]
	ds_read_b128 v[84:87], v178 offset:52416
	s_waitcnt lgkmcnt(0)
	v_mfma_f32_16x16x32_bf16 v[42:45], v[66:69], v[84:87], v[42:45]
	ds_read_b128 v[84:87], v178 offset:56576
	s_waitcnt lgkmcnt(0)
	v_mfma_f32_16x16x32_bf16 v[38:41], v[78:81], v[84:87], v[38:41]
	ds_read_b128 v[84:87], v178 offset:56640
	s_waitcnt lgkmcnt(0)
	v_mfma_f32_16x16x32_bf16 v[38:41], v[74:77], v[84:87], v[38:41]
	ds_read_b128 v[84:87], v178 offset:56704
	s_waitcnt lgkmcnt(0)
	v_mfma_f32_16x16x32_bf16 v[38:41], v[70:73], v[84:87], v[38:41]
	ds_read_b128 v[84:87], v178 offset:56768
	s_waitcnt lgkmcnt(0)
	v_mfma_f32_16x16x32_bf16 v[38:41], v[66:69], v[84:87], v[38:41]
	ds_read_b128 v[84:87], v178 offset:60928
	s_waitcnt lgkmcnt(0)
	v_mfma_f32_16x16x32_bf16 v[34:37], v[78:81], v[84:87], v[34:37]
	ds_read_b128 v[84:87], v178 offset:60992
	s_waitcnt lgkmcnt(0)
	v_mfma_f32_16x16x32_bf16 v[34:37], v[74:77], v[84:87], v[34:37]
	ds_read_b128 v[84:87], v178 offset:61056
	s_waitcnt lgkmcnt(0)
	v_mfma_f32_16x16x32_bf16 v[34:37], v[70:73], v[84:87], v[34:37]
	ds_read_b128 v[84:87], v178 offset:61120
	s_waitcnt lgkmcnt(0)
	v_mfma_f32_16x16x32_bf16 v[34:37], v[66:69], v[84:87], v[34:37]
	ds_read_b128 v[84:87], v178 offset:65280
	s_waitcnt lgkmcnt(0)
	v_mfma_f32_16x16x32_bf16 v[54:57], v[78:81], v[84:87], v[54:57]
	ds_read_b128 v[78:81], v178 offset:65344
	s_waitcnt lgkmcnt(0)
	v_mfma_f32_16x16x32_bf16 v[54:57], v[74:77], v[78:81], v[54:57]
	ds_read_b128 v[74:77], v178 offset:65408
	s_waitcnt lgkmcnt(0)
	v_mfma_f32_16x16x32_bf16 v[54:57], v[70:73], v[74:77], v[54:57]
	ds_read_b128 v[70:73], v178 offset:65472
	s_waitcnt lgkmcnt(0)
	v_mfma_f32_16x16x32_bf16 v[54:57], v[66:69], v[70:73], v[54:57]
	v_lshrrev_b32_e32 v66, 6, v163
	v_and_b32_e32 v67, 15, v163
	v_lshl_add_u32 v66, v66, 4, v67
	v_bfe_u32 v67, v163, 4, 2
	v_mul_u32_u24_e32 v68, 0x110, v66
	v_lshl_add_u32 v67, v67, 4, v68
	v_lshlrev_b32_e32 v66, 2, v66
	v_add_u32_e32 v66, 0x22600, v66
	v_mov_b32_e32 v76, 0x3f803f80
	v_mov_b32_e32 v77, 0x3f803f80
	v_mov_b32_e32 v78, 0x3f803f80
	v_mov_b32_e32 v79, 0x3f803f80
	ds_read_b128 v[68:71], v67 offset:34816
	ds_read_b128 v[72:75], v67 offset:34880
	s_waitcnt lgkmcnt(1)
	v_mfma_f32_16x16x32_bf16 v[84:87], v[76:79], v[68:71], 0
	ds_read_b128 v[68:71], v67 offset:34944
	s_waitcnt lgkmcnt(1)
	v_mfma_f32_16x16x32_bf16 v[84:87], v[76:79], v[72:75], v[84:87]
	ds_read_b128 v[72:75], v67 offset:35008
	ds_read_b32 v67, v66
	s_waitcnt lgkmcnt(2)
	v_mfma_f32_16x16x32_bf16 v[84:87], v[76:79], v[68:71], v[84:87]
	s_waitcnt lgkmcnt(1)
	v_mfma_f32_16x16x32_bf16 v[84:87], v[76:79], v[72:75], v[84:87]
	s_waitcnt lgkmcnt(0)
	s_nop 7
	s_nop 1
	v_fmac_f32_e32 v84, v82, v67
.LBB0_667:
	s_barrier
	s_mov_b64 exec, 0xffff
	ds_write_b32 v66, v84
	s_mov_b64 exec, -1
	v_cvt_pk_bf16_f32 v66, v46, s0
	ds_write_b16 v105, v66
	v_cvt_pk_bf16_f32 v66, v47, s0
	ds_write_b16 v105, v66 offset:272
	v_cvt_pk_bf16_f32 v66, v48, s0
	ds_write_b16 v105, v66 offset:544
	v_cvt_pk_bf16_f32 v66, v49, s0
	ds_write_b16 v105, v66 offset:816
	v_cvt_pk_bf16_f32 v66, v62, s0
	ds_write_b16 v105, v66 offset:32
	v_cvt_pk_bf16_f32 v66, v63, s0
	ds_write_b16 v105, v66 offset:304
	v_cvt_pk_bf16_f32 v66, v64, s0
	ds_write_b16 v105, v66 offset:576
	v_cvt_pk_bf16_f32 v66, v65, s0
	ds_write_b16 v105, v66 offset:848
	v_cvt_pk_bf16_f32 v66, v58, s0
	ds_write_b16 v105, v66 offset:64
	v_cvt_pk_bf16_f32 v66, v59, s0
	ds_write_b16 v105, v66 offset:336
	v_cvt_pk_bf16_f32 v66, v60, s0
	ds_write_b16 v105, v66 offset:608
	v_cvt_pk_bf16_f32 v66, v61, s0
	ds_write_b16 v105, v66 offset:880
	v_cvt_pk_bf16_f32 v66, v50, s0
	ds_write_b16 v105, v66 offset:96
	v_cvt_pk_bf16_f32 v66, v51, s0
	ds_write_b16 v105, v66 offset:368
	v_cvt_pk_bf16_f32 v66, v52, s0
	ds_write_b16 v105, v66 offset:640
	v_cvt_pk_bf16_f32 v66, v53, s0
	ds_write_b16 v105, v66 offset:912
	v_cvt_pk_bf16_f32 v66, v42, s0
	ds_write_b16 v105, v66 offset:128
	v_cvt_pk_bf16_f32 v66, v43, s0
	ds_write_b16 v105, v66 offset:400
	v_cvt_pk_bf16_f32 v66, v44, s0
	ds_write_b16 v105, v66 offset:672
	v_cvt_pk_bf16_f32 v66, v45, s0
	ds_write_b16 v105, v66 offset:944
	v_cvt_pk_bf16_f32 v66, v38, s0
	ds_write_b16 v105, v66 offset:160
	v_cvt_pk_bf16_f32 v66, v39, s0
	ds_write_b16 v105, v66 offset:432
	v_cvt_pk_bf16_f32 v66, v40, s0
	ds_write_b16 v105, v66 offset:704
	v_cvt_pk_bf16_f32 v66, v41, s0
	ds_write_b16 v105, v66 offset:976
	v_cvt_pk_bf16_f32 v66, v34, s0
	ds_write_b16 v105, v66 offset:192
	v_cvt_pk_bf16_f32 v66, v35, s0
	ds_write_b16 v105, v66 offset:464
	v_cvt_pk_bf16_f32 v66, v36, s0
	ds_write_b16 v105, v66 offset:736
	v_cvt_pk_bf16_f32 v66, v37, s0
	ds_write_b16 v105, v66 offset:1008
	v_cvt_pk_bf16_f32 v66, v54, s0
	ds_write_b16 v105, v66 offset:224
	v_cvt_pk_bf16_f32 v66, v55, s0
	ds_write_b16 v105, v66 offset:496
	v_cvt_pk_bf16_f32 v66, v56, s0
	v_add_f32_e32 v181, v179, v180
	ds_write_b16 v105, v66 offset:768
	v_cvt_pk_bf16_f32 v66, v57, s0
	s_movk_i32 s0, 0x80
	s_mov_b64 s[96:97], 0
	s_and_b64 vcc, exec, s[2:3]
	ds_write_b16 v105, v66 offset:1040
	s_cbranch_vccnz .LBB0_697
	s_mov_b64 s[2:3], -1
	s_and_saveexec_b64 s[90:91], s[10:11]
	s_cbranch_execnz .LBB0_654
	s_branch .LBB0_655

.LBB0_691:
	ds_read_b32 v155, v125
	s_waitcnt vmcnt(3)
	v_and_b32_e32 v187, 0xffff0000, v78
	v_lshlrev_b32_e32 v186, 16, v78
	s_waitcnt vmcnt(2)
	v_and_b32_e32 v191, 0xffff0000, v74
	v_and_b32_e32 v190, 0xffff0000, v80
	s_waitcnt lgkmcnt(0)
	v_sub_f32_e32 v82, v154, v155
	v_mul_f32_e32 v156, 0x3fb8aa3b, v82
	ds_read_b128 v[82:85], v138
	ds_read_b128 v[86:89], v138 offset:1088
	ds_read_b128 v[90:93], v138 offset:64
	ds_read_b128 v[94:97], v138 offset:1152
	v_lshlrev_b64 v[110:111], 10, v[110:111]
	s_waitcnt lgkmcnt(3)
	v_mfma_f32_16x16x32_bf16 v[82:85], v[82:85], v[78:81], 0
	s_mov_b32 s90, 0
	s_waitcnt lgkmcnt(2)
	v_mfma_f32_16x16x32_bf16 v[86:89], v[86:89], v[78:81], 0
	s_waitcnt lgkmcnt(1)
	v_mfma_f32_16x16x32_bf16 v[82:85], v[90:93], v[74:77], v[82:85]
	s_waitcnt lgkmcnt(0)
	v_mfma_f32_16x16x32_bf16 v[86:89], v[94:97], v[74:77], v[86:89]
	ds_read_b128 v[90:93], v138 offset:128
	ds_read_b128 v[94:97], v138 offset:1216
	s_waitcnt vmcnt(1) lgkmcnt(1)
	v_mfma_f32_16x16x32_bf16 v[82:85], v[90:93], v[70:73], v[82:85]
	s_waitcnt lgkmcnt(0)
	v_mfma_f32_16x16x32_bf16 v[86:89], v[94:97], v[70:73], v[86:89]
	ds_read_b128 v[90:93], v138 offset:192
	ds_read_b128 v[94:97], v138 offset:1280
	s_waitcnt vmcnt(0) lgkmcnt(1)
	v_mfma_f32_16x16x32_bf16 v[82:85], v[90:93], v[66:69], v[82:85]
	s_waitcnt lgkmcnt(0)
	v_mfma_f32_16x16x32_bf16 v[86:89], v[94:97], v[66:69], v[86:89]
	ds_read_b128 v[90:93], v127
	ds_read_b128 v[94:97], v127 offset:16
	s_waitcnt lgkmcnt(1)
	v_sub_f32_e32 v90, v90, v155
	v_sub_f32_e32 v91, v91, v155
	v_mul_f32_e32 v90, 0x3fb8aa3b, v90
	v_mul_f32_e32 v91, 0x3fb8aa3b, v91
	v_exp_f32_e32 v90, v90
	v_exp_f32_e32 v91, v91
	v_mul_f32_e32 v82, v82, v90
	v_mul_f32_e32 v83, v83, v91
	v_cndmask_b32_e64 v90, v82, 0, s[24:25]
	s_waitcnt lgkmcnt(0)
	v_sub_f32_e32 v82, v94, v155
	v_cndmask_b32_e64 v91, 0, v83, s[26:27]
	v_sub_f32_e32 v83, v95, v155
	v_mul_f32_e32 v82, 0x3fb8aa3b, v82
	v_mul_f32_e32 v83, 0x3fb8aa3b, v83
	v_exp_f32_e32 v82, v82
	v_exp_f32_e32 v83, v83
	s_nop 0
	v_pk_mul_f32 v[82:83], v[86:87], v[82:83]
	s_nop 0
	v_cndmask_b32_e64 v95, v83, 0, s[28:29]
	v_sub_f32_e32 v83, v96, v155
	v_mul_f32_e32 v83, 0x3fb8aa3b, v83
	v_cndmask_b32_e64 v98, v82, 0, s[30:31]
	v_sub_f32_e32 v82, v92, v155
	v_exp_f32_e32 v86, v83
	v_sub_f32_e32 v83, v93, v155
	v_mul_f32_e32 v82, 0x3fb8aa3b, v82
	v_mul_f32_e32 v83, 0x3fb8aa3b, v83
	v_exp_f32_e32 v82, v82
	v_exp_f32_e32 v83, v83
	s_nop 0
	v_pk_mul_f32 v[82:83], v[84:85], v[82:83]
	s_nop 0
	v_cndmask_b32_e64 v85, v82, 0, s[36:37]
	v_sub_f32_e32 v82, v97, v155
	v_mul_f32_e32 v82, 0x3fb8aa3b, v82
	v_exp_f32_e32 v87, v82
	v_cndmask_b32_e64 v84, v83, 0, s[34:35]
	v_pk_mul_f32 v[82:83], v[88:89], v[86:87]
	s_nop 0
	v_cndmask_b32_e64 v87, v82, 0, s[40:41]
	v_add_f32_e32 v82, 0, v90
	v_add_f32_e32 v82, v91, v82
	v_add_f32_e32 v82, v85, v82
	v_add_f32_e32 v82, v84, v82
	v_add_f32_e32 v82, v98, v82
	v_add_f32_e32 v82, v95, v82
	v_cndmask_b32_e64 v86, v83, 0, s[38:39]
	v_add_f32_e32 v82, v87, v82
	v_add_f32_e32 v94, v86, v82
	v_cvt_pk_bf16_f32 v82, v90, v91
	v_cvt_pk_bf16_f32 v83, v85, v84
	v_cvt_pk_bf16_f32 v85, v87, v86
	ds_read_b128 v[86:89], v138 offset:8704
	ds_read_b128 v[90:93], v138 offset:9792
	v_cvt_pk_bf16_f32 v84, v98, v95
	ds_read_b128 v[96:99], v138 offset:8768
	ds_read_b128 v[158:161], v138 offset:9856
	s_waitcnt lgkmcnt(3)
	v_mfma_f32_16x16x32_bf16 v[86:89], v[86:89], v[78:81], 0
	s_waitcnt lgkmcnt(2)
	v_mfma_f32_16x16x32_bf16 v[90:93], v[90:93], v[78:81], 0
	s_waitcnt lgkmcnt(1)
	v_mfma_f32_16x16x32_bf16 v[86:89], v[96:99], v[74:77], v[86:89]
	s_waitcnt lgkmcnt(0)
	v_mfma_f32_16x16x32_bf16 v[90:93], v[158:161], v[74:77], v[90:93]
	ds_read_b128 v[96:99], v138 offset:8832
	ds_read_b128 v[158:161], v138 offset:9920
	s_waitcnt lgkmcnt(1)
	v_mfma_f32_16x16x32_bf16 v[86:89], v[96:99], v[70:73], v[86:89]
	s_waitcnt lgkmcnt(0)
	v_mfma_f32_16x16x32_bf16 v[96:99], v[158:161], v[70:73], v[90:93]
	s_nop 2
	ds_read_b128 v[90:93], v138 offset:8896
	ds_read_b128 v[158:161], v138 offset:9984
	s_waitcnt lgkmcnt(1)
	v_mfma_f32_16x16x32_bf16 v[90:93], v[90:93], v[66:69], v[86:89]
	s_waitcnt lgkmcnt(0)
	v_mfma_f32_16x16x32_bf16 v[86:89], v[158:161], v[66:69], v[96:99]
	s_nop 2
	ds_read_b128 v[96:99], v127 offset:128
	ds_read_b128 v[158:161], v127 offset:144
	s_waitcnt lgkmcnt(1)
	v_sub_f32_e32 v95, v96, v155
	v_mul_f32_e32 v95, 0x3fb8aa3b, v95
	v_exp_f32_e32 v96, v95
	s_waitcnt lgkmcnt(0)
	v_sub_f32_e32 v95, v158, v155
	v_mul_f32_e32 v95, 0x3fb8aa3b, v95
	v_exp_f32_e32 v100, v95
	v_sub_f32_e32 v95, v97, v155
	v_mul_f32_e32 v95, 0x3fb8aa3b, v95
	v_exp_f32_e32 v97, v95
	s_nop 0
	v_pk_mul_f32 v[90:91], v[90:91], v[96:97]
	s_nop 0
	v_cndmask_b32_e64 v96, v90, 0, s[44:45]
	v_sub_f32_e32 v90, v159, v155
	v_mul_f32_e32 v90, 0x3fb8aa3b, v90
	v_exp_f32_e32 v101, v90
	v_cndmask_b32_e64 v95, v91, 0, s[42:43]
	v_pk_mul_f32 v[86:87], v[86:87], v[100:101]
	s_nop 0
	v_cndmask_b32_e64 v97, v87, 0, s[46:47]
	v_sub_f32_e32 v87, v160, v155
	v_mul_f32_e32 v87, 0x3fb8aa3b, v87
	v_cndmask_b32_e64 v100, v86, 0, s[48:49]
	v_sub_f32_e32 v86, v98, v155
	v_exp_f32_e32 v90, v87
	v_sub_f32_e32 v87, v99, v155
	v_mul_f32_e32 v86, 0x3fb8aa3b, v86
	v_mul_f32_e32 v87, 0x3fb8aa3b, v87
	v_exp_f32_e32 v86, v86
	v_exp_f32_e32 v87, v87
	s_nop 0
	v_pk_mul_f32 v[86:87], v[92:93], v[86:87]
	s_nop 0
	v_cndmask_b32_e64 v93, v86, 0, s[52:53]
	v_sub_f32_e32 v86, v161, v155
	v_mul_f32_e32 v86, 0x3fb8aa3b, v86
	v_exp_f32_e32 v91, v86
	v_cndmask_b32_e64 v92, v87, 0, s[50:51]
	v_pk_mul_f32 v[86:87], v[88:89], v[90:91]
	s_nop 0
	v_cndmask_b32_e64 v90, v86, 0, s[56:57]
	v_add_f32_e32 v86, v94, v96
	v_add_f32_e32 v86, v95, v86
	v_add_f32_e32 v86, v93, v86
	v_add_f32_e32 v86, v92, v86
	v_add_f32_e32 v86, v100, v86
	v_add_f32_e32 v86, v97, v86
	v_cndmask_b32_e64 v89, v87, 0, s[54:55]
	v_add_f32_e32 v86, v90, v86
	v_add_f32_e32 v98, v89, v86
	v_cvt_pk_bf16_f32 v86, v96, v95
	v_cvt_pk_bf16_f32 v87, v93, v92
	v_cvt_pk_bf16_f32 v88, v100, v97
	v_cvt_pk_bf16_f32 v89, v90, v89
	ds_read_b128 v[90:93], v138 offset:17408
	ds_read_b128 v[94:97], v138 offset:18496
	ds_read_b128 v[158:161], v138 offset:17472
	ds_read_b128 v[176:179], v138 offset:18560
	s_waitcnt lgkmcnt(3)
	v_mfma_f32_16x16x32_bf16 v[90:93], v[90:93], v[78:81], 0
	s_waitcnt lgkmcnt(2)
	v_mfma_f32_16x16x32_bf16 v[94:97], v[94:97], v[78:81], 0
	s_waitcnt lgkmcnt(1)
	v_mfma_f32_16x16x32_bf16 v[90:93], v[158:161], v[74:77], v[90:93]
	s_waitcnt lgkmcnt(0)
	v_mfma_f32_16x16x32_bf16 v[94:97], v[176:179], v[74:77], v[94:97]
	ds_read_b128 v[158:161], v138 offset:17536
	ds_read_b128 v[176:179], v138 offset:18624
	s_waitcnt lgkmcnt(1)
	v_mfma_f32_16x16x32_bf16 v[90:93], v[158:161], v[70:73], v[90:93]
	s_waitcnt lgkmcnt(0)
	v_mfma_f32_16x16x32_bf16 v[158:161], v[176:179], v[70:73], v[94:97]
	s_nop 2
	ds_read_b128 v[94:97], v138 offset:17600
	ds_read_b128 v[176:179], v138 offset:18688
	s_waitcnt lgkmcnt(1)
	v_mfma_f32_16x16x32_bf16 v[94:97], v[94:97], v[66:69], v[90:93]
	s_waitcnt lgkmcnt(0)
	v_mfma_f32_16x16x32_bf16 v[90:93], v[176:179], v[66:69], v[158:161]
	s_nop 2
	ds_read_b128 v[158:161], v127 offset:256
	ds_read_b128 v[176:179], v127 offset:272
	s_waitcnt lgkmcnt(1)
	v_sub_f32_e32 v99, v158, v155
	v_mul_f32_e32 v99, 0x3fb8aa3b, v99
	v_exp_f32_e32 v100, v99
	s_waitcnt lgkmcnt(0)
	v_sub_f32_e32 v99, v176, v155
	v_mul_f32_e32 v99, 0x3fb8aa3b, v99
	v_exp_f32_e32 v158, v99
	v_sub_f32_e32 v99, v159, v155
	v_mul_f32_e32 v99, 0x3fb8aa3b, v99
	v_exp_f32_e32 v101, v99
	s_nop 0
	v_pk_mul_f32 v[94:95], v[94:95], v[100:101]
	s_nop 0
	v_cndmask_b32_e64 v100, v94, 0, s[60:61]
	v_sub_f32_e32 v94, v177, v155
	v_mul_f32_e32 v94, 0x3fb8aa3b, v94
	v_exp_f32_e32 v159, v94
	v_cndmask_b32_e64 v99, v95, 0, s[58:59]
	v_pk_mul_f32 v[90:91], v[90:91], v[158:159]
	s_nop 0
	v_cndmask_b32_e64 v101, v91, 0, s[62:63]
	v_sub_f32_e32 v91, v178, v155
	v_mul_f32_e32 v91, 0x3fb8aa3b, v91
	v_cndmask_b32_e64 v158, v90, 0, s[64:65]
	v_sub_f32_e32 v90, v160, v155
	v_exp_f32_e32 v94, v91
	v_sub_f32_e32 v91, v161, v155
	v_mul_f32_e32 v90, 0x3fb8aa3b, v90
	v_mul_f32_e32 v91, 0x3fb8aa3b, v91
	v_exp_f32_e32 v90, v90
	v_exp_f32_e32 v91, v91
	s_nop 0
	v_pk_mul_f32 v[90:91], v[96:97], v[90:91]
	s_nop 0
	v_cndmask_b32_e64 v97, v90, 0, s[68:69]
	v_sub_f32_e32 v90, v179, v155
	v_mul_f32_e32 v90, 0x3fb8aa3b, v90
	v_exp_f32_e32 v95, v90
	v_cndmask_b32_e64 v96, v91, 0, s[66:67]
	v_pk_mul_f32 v[90:91], v[92:93], v[94:95]
	s_nop 0
	v_cndmask_b32_e64 v94, v90, 0, s[72:73]
	v_add_f32_e32 v90, v98, v100
	v_add_f32_e32 v90, v99, v90
	v_add_f32_e32 v90, v97, v90
	v_add_f32_e32 v90, v96, v90
	v_add_f32_e32 v90, v158, v90
	v_add_f32_e32 v90, v101, v90
	v_cndmask_b32_e64 v93, v91, 0, s[70:71]
	v_add_f32_e32 v90, v94, v90
	v_add_f32_e32 v157, v93, v90
	v_cvt_pk_bf16_f32 v90, v100, v99
	v_cvt_pk_bf16_f32 v91, v97, v96
	v_cvt_pk_bf16_f32 v92, v158, v101
	v_cvt_pk_bf16_f32 v93, v94, v93
	ds_read_b128 v[94:97], v138 offset:26112
	ds_read_b128 v[98:101], v138 offset:27200
	ds_read_b128 v[158:161], v138 offset:26176
	ds_read_b128 v[176:179], v138 offset:27264
	s_waitcnt lgkmcnt(3)
	v_mfma_f32_16x16x32_bf16 v[94:97], v[94:97], v[78:81], 0
	s_waitcnt lgkmcnt(2)
	v_mfma_f32_16x16x32_bf16 v[98:101], v[98:101], v[78:81], 0
	s_waitcnt lgkmcnt(1)
	v_mfma_f32_16x16x32_bf16 v[94:97], v[158:161], v[74:77], v[94:97]
	s_waitcnt lgkmcnt(0)
	v_mfma_f32_16x16x32_bf16 v[98:101], v[176:179], v[74:77], v[98:101]
	ds_read_b128 v[158:161], v138 offset:26240
	ds_read_b128 v[176:179], v138 offset:27328
	s_waitcnt lgkmcnt(1)
	v_mfma_f32_16x16x32_bf16 v[94:97], v[158:161], v[70:73], v[94:97]
	s_waitcnt lgkmcnt(0)
	v_mfma_f32_16x16x32_bf16 v[158:161], v[176:179], v[70:73], v[98:101]
	s_nop 2
	ds_read_b128 v[98:101], v138 offset:26304
	ds_read_b128 v[176:179], v138 offset:27392
	s_waitcnt lgkmcnt(1)
	v_mfma_f32_16x16x32_bf16 v[98:101], v[98:101], v[66:69], v[94:97]
	s_waitcnt lgkmcnt(0)
	v_mfma_f32_16x16x32_bf16 v[94:97], v[176:179], v[66:69], v[158:161]
	s_nop 2
	ds_read_b128 v[158:161], v127 offset:384
	ds_read_b128 v[176:179], v127 offset:400
	s_waitcnt lgkmcnt(1)
	v_sub_f32_e32 v158, v158, v155
	v_sub_f32_e32 v159, v159, v155
	v_mul_f32_e32 v158, 0x3fb8aa3b, v158
	v_mul_f32_e32 v159, 0x3fb8aa3b, v159
	v_exp_f32_e32 v158, v158
	v_exp_f32_e32 v159, v159
	s_waitcnt lgkmcnt(0)
	v_sub_f32_e32 v169, v176, v155
	v_mul_f32_e32 v169, 0x3fb8aa3b, v169
	v_exp_f32_e32 v176, v169
	v_pk_mul_f32 v[98:99], v[98:99], v[158:159]
	s_nop 0
	v_cndmask_b32_e64 v159, v98, 0, s[76:77]
	v_sub_f32_e32 v98, v177, v155
	v_mul_f32_e32 v98, 0x3fb8aa3b, v98
	v_exp_f32_e32 v177, v98
	v_cndmask_b32_e64 v158, v99, 0, s[74:75]
	v_pk_mul_f32 v[94:95], v[94:95], v[176:177]
	s_nop 0
	v_cndmask_b32_e64 v176, v95, 0, s[78:79]
	v_sub_f32_e32 v95, v178, v155
	v_mul_f32_e32 v95, 0x3fb8aa3b, v95
	v_cndmask_b32_e64 v180, v94, 0, s[80:81]
	v_sub_f32_e32 v94, v160, v155
	v_exp_f32_e32 v98, v95
	v_sub_f32_e32 v95, v161, v155
	v_mul_f32_e32 v94, 0x3fb8aa3b, v94
	v_mul_f32_e32 v95, 0x3fb8aa3b, v95
	v_exp_f32_e32 v94, v94
	v_exp_f32_e32 v95, v95
	s_nop 0
	v_pk_mul_f32 v[94:95], v[100:101], v[94:95]
	s_nop 0
	v_cndmask_b32_e64 v101, v94, 0, s[84:85]
	v_sub_f32_e32 v94, v179, v155
	v_mul_f32_e32 v94, 0x3fb8aa3b, v94
	v_exp_f32_e32 v99, v94
	v_cndmask_b32_e64 v100, v95, 0, s[82:83]
	v_pk_mul_f32 v[94:95], v[96:97], v[98:99]
	s_nop 0
	v_cndmask_b32_e64 v182, v94, 0, s[88:89]
	v_add_f32_e32 v94, v157, v159
	v_add_f32_e32 v94, v158, v94
	v_add_u32_e32 v98, 0, v126
	v_add_f32_e32 v94, v101, v94
	v_add_u32_e32 v157, 0x22600, v98
	v_cndmask_b32_e64 v178, v95, 0, s[86:87]
	v_add_f32_e32 v184, v100, v94
	v_cvt_pk_bf16_f32 v94, v159, v158
	v_cvt_pk_bf16_f32 v95, v101, v100
	ds_read_b128 v[98:101], v157
	ds_read_b128 v[158:161], v157 offset:16
	v_cvt_pk_bf16_f32 v96, v180, v176
	v_cvt_pk_bf16_f32 v97, v182, v178
	s_waitcnt lgkmcnt(1)
	v_pk_mul_f32 v[98:99], v[98:99], v[186:187]
	v_and_b32_e32 v187, 0xffff0000, v79
	v_lshlrev_b32_e32 v186, 16, v79
	v_pk_mul_f32 v[100:101], v[100:101], v[186:187]
	v_add_f32_e32 v98, v98, v99
	v_add_f32_e32 v98, v100, v98
	v_add_f32_e32 v98, v101, v98
	v_add_f32_e32 v169, 0, v98
	ds_read_b128 v[98:101], v157 offset:128
	v_lshlrev_b32_e32 v187, 16, v74
	v_lshlrev_b32_e32 v186, 16, v80
	s_waitcnt lgkmcnt(1)
	v_mov_b32_e32 v188, v158
	v_lshlrev_b32_e32 v158, 16, v81
	s_waitcnt lgkmcnt(0)
	v_mov_b32_e32 v189, v98
	v_mov_b32_e32 v98, v159
	v_pk_mul_f32 v[98:99], v[98:99], v[190:191]
	v_lshlrev_b32_e32 v159, 16, v75
	v_pk_fma_f32 v[98:99], v[188:189], v[186:187], v[98:99]
	v_mov_b32_e32 v186, v160
	v_mov_b32_e32 v187, v100
	v_pk_fma_f32 v[98:99], v[186:187], v[158:159], v[98:99]
	v_and_b32_e32 v159, 0xffff0000, v75
	v_and_b32_e32 v158, 0xffff0000, v81
	v_mov_b32_e32 v100, v161
	v_pk_fma_f32 v[98:99], v[100:101], v[158:159], v[98:99]
	v_and_b32_e32 v191, 0xffff0000, v70
	v_add_f32_e32 v98, v169, v98
	v_add_f32_e32 v169, v98, v99
	ds_read_b128 v[98:101], v157 offset:144
	ds_read_b128 v[158:161], v157 offset:256
	v_and_b32_e32 v190, 0xffff0000, v76
	v_lshlrev_b32_e32 v187, 16, v70
	v_lshlrev_b32_e32 v186, 16, v76
	s_waitcnt lgkmcnt(1)
	v_mov_b32_e32 v188, v98
	s_waitcnt lgkmcnt(0)
	v_mov_b32_e32 v189, v158
	v_mov_b32_e32 v158, v99
	v_pk_mul_f32 v[98:99], v[158:159], v[190:191]
	v_lshlrev_b32_e32 v159, 16, v71
	v_pk_fma_f32 v[98:99], v[188:189], v[186:187], v[98:99]
	v_lshlrev_b32_e32 v158, 16, v77
	v_mov_b32_e32 v186, v100
	v_mov_b32_e32 v187, v160
	v_pk_fma_f32 v[98:99], v[186:187], v[158:159], v[98:99]
	v_and_b32_e32 v159, 0xffff0000, v71
	v_and_b32_e32 v158, 0xffff0000, v77
	v_mov_b32_e32 v160, v101
	v_pk_fma_f32 v[98:99], v[160:161], v[158:159], v[98:99]
	v_and_b32_e32 v191, 0xffff0000, v66
	v_add_f32_e32 v98, v169, v98
	v_add_f32_e32 v169, v98, v99
	ds_read_b128 v[98:101], v157 offset:272
	ds_read_b128 v[158:161], v157 offset:384
	v_and_b32_e32 v190, 0xffff0000, v72
	v_lshlrev_b32_e32 v187, 16, v66
	v_lshlrev_b32_e32 v186, 16, v72
	s_waitcnt lgkmcnt(1)
	v_mov_b32_e32 v188, v98
	s_waitcnt lgkmcnt(0)
	v_mov_b32_e32 v189, v158
	v_mov_b32_e32 v158, v99
	v_pk_mul_f32 v[98:99], v[158:159], v[190:191]
	v_lshlrev_b32_e32 v159, 16, v67
	v_pk_fma_f32 v[98:99], v[188:189], v[186:187], v[98:99]
	v_lshlrev_b32_e32 v158, 16, v73
	v_mov_b32_e32 v186, v100
	v_mov_b32_e32 v187, v160
	v_pk_fma_f32 v[98:99], v[186:187], v[158:159], v[98:99]
	v_and_b32_e32 v159, 0xffff0000, v67
	v_and_b32_e32 v158, 0xffff0000, v73
	v_mov_b32_e32 v160, v101
	v_pk_fma_f32 v[98:99], v[160:161], v[158:159], v[98:99]
	s_nop 0
	v_add_f32_e32 v98, v169, v98
	v_add_f32_e32 v179, v98, v99
	ds_read_b128 v[98:101], v157 offset:400
	v_lshlrev_b32_e32 v157, 16, v68
	s_waitcnt lgkmcnt(0)
	v_mul_f32_e32 v181, v98, v157
	v_and_b32_e32 v98, 0xffff0000, v68
	v_mul_f32_e32 v185, v99, v98
	v_lshlrev_b32_e32 v98, 16, v69
	v_mul_f32_e32 v177, v100, v98
	v_and_b32_e32 v98, 0xffff0000, v69
	v_mul_f32_e32 v183, v101, v98
	v_pk_add_f32 v[100:101], v[180:181], v[184:185]
	v_exp_f32_e32 v98, v156
	v_pk_add_f32 v[100:101], v[176:177], v[100:101]
	ds_read_b32 v99, v130
	v_pk_add_f32 v[100:101], v[182:183], v[100:101]
	s_nop 0
	v_pk_add_f32 v[100:101], v[178:179], v[100:101]
	ds_bpermute_b32 v156, v128, v100
	ds_bpermute_b32 v157, v128, v101
	ds_read_b128 v[176:179], v148 offset:64
	s_waitcnt lgkmcnt(3)
	v_add_f32_e32 v99, v155, v99
	v_mul_f32_e32 v99, 0xbfb8aa3b, v99
	v_exp_f32_e32 v99, v99
	s_waitcnt lgkmcnt(1)
	v_pk_add_f32 v[100:101], v[100:101], v[156:157]
	ds_bpermute_b32 v156, v129, v100
	ds_bpermute_b32 v157, v129, v101
	s_waitcnt lgkmcnt(0)
	v_pk_add_f32 v[100:101], v[100:101], v[156:157]
	s_nop 0
	v_fmac_f32_e32 v100, v98, v101
	v_max_f32_e64 v99, |v100|, v99
	v_div_scale_f32 v100, s[96:97], v99, v99, 1.0
	v_rcp_f32_e32 v101, v100
	v_readlane_b32 s96, v254, 25
	v_readlane_b32 s97, v254, 26
	s_load_dwordx2 s[96:97], s[96:97], 0x118
	v_fma_f32 v155, -v100, v101, 1.0
	v_fmac_f32_e32 v101, v155, v101
	v_div_scale_f32 v155, vcc, 1.0, v99, 1.0
	v_mul_f32_e32 v156, v155, v101
	v_fma_f32 v157, -v100, v156, v155
	v_fmac_f32_e32 v156, v157, v101
	v_fma_f32 v100, -v100, v156, v155
	v_div_fmas_f32 v100, v100, v101, v156
	ds_read_b128 v[156:159], v148
	s_waitcnt lgkmcnt(0)
	v_mfma_f32_16x16x32_bf16 v[156:159], v[156:159], v[78:81], 0
	v_lshl_add_u64 v[112:113], s[96:97], 0, v[112:113]
	s_mov_b64 s[96:97], 0x2134200
	v_lshl_add_u64 v[112:113], v[112:113], 0, s[96:97]
	v_mfma_f32_16x16x32_bf16 v[156:159], v[176:179], v[74:77], v[156:159]
	ds_read_b128 v[176:179], v148 offset:128
	v_readlane_b32 s96, v254, 60
	v_readlane_b32 s97, v254, 61
	s_waitcnt lgkmcnt(0)
	v_mfma_f32_16x16x32_bf16 v[156:159], v[176:179], v[70:73], v[156:159]
	ds_read_b128 v[176:179], v148 offset:192
	v_lshl_add_u64 v[110:111], s[96:97], 0, v[110:111]
	v_readlane_b32 s96, v254, 19
	s_waitcnt lgkmcnt(0)
	v_mfma_f32_16x16x32_bf16 v[156:159], v[176:179], v[66:69], v[156:159]
	ds_read_b128 v[176:179], v149
	v_div_fixup_f32 v100, v100, v99, 1.0
	v_cndmask_b32_e64 v111, v111, v113, s[6:7]
	s_nop 4
	v_pk_mul_f32 v[158:159], v[98:99], v[158:159] op_sel_hi:[0,1]
	v_pk_mul_f32 v[156:157], v[98:99], v[156:157] op_sel_hi:[0,1]
	v_cndmask_b32_e64 v110, v110, v112, s[6:7]
	v_readlane_b32 s97, v254, 20
	s_waitcnt lgkmcnt(0)
	v_mfma_f32_16x16x32_bf16 v[156:159], v[176:179], v[82:85], v[156:159]
	ds_read_b128 v[176:179], v149 offset:64
	v_lshl_add_u64 v[110:111], v[110:111], 0, s[96:97]
	v_lshl_add_u64 v[110:111], v[110:111], 0, v[0:1]
	s_waitcnt lgkmcnt(0)
	v_mfma_f32_16x16x32_bf16 v[156:159], v[176:179], v[86:89], v[156:159]
	ds_read_b128 v[176:179], v149 offset:128
	s_waitcnt lgkmcnt(0)
	v_mfma_f32_16x16x32_bf16 v[156:159], v[176:179], v[90:93], v[156:159]
	ds_read_b128 v[176:179], v149 offset:192
	s_waitcnt lgkmcnt(0)
	v_mfma_f32_16x16x32_bf16 v[156:159], v[176:179], v[94:97], v[156:159]
	ds_read_b128 v[176:179], v148 offset:4416
	s_nop 6
	v_pk_mul_f32 v[112:113], v[100:101], v[158:159] op_sel_hi:[0,1]
	v_pk_mul_f32 v[156:157], v[100:101], v[156:157] op_sel_hi:[0,1]
	v_cvt_pk_bf16_f32 v156, v156, v157
	v_cvt_pk_bf16_f32 v157, v112, v113
	global_store_dwordx2 v[110:111], v[156:157], off
	ds_read_b128 v[156:159], v148 offset:4352
	s_waitcnt lgkmcnt(0)
	v_mfma_f32_16x16x32_bf16 v[156:159], v[156:159], v[78:81], 0
	v_mfma_f32_16x16x32_bf16 v[156:159], v[176:179], v[74:77], v[156:159]
	ds_read_b128 v[176:179], v148 offset:4480
	s_waitcnt lgkmcnt(0)
	v_mfma_f32_16x16x32_bf16 v[156:159], v[176:179], v[70:73], v[156:159]
	ds_read_b128 v[176:179], v148 offset:4544
	s_waitcnt lgkmcnt(0)
	v_mfma_f32_16x16x32_bf16 v[156:159], v[176:179], v[66:69], v[156:159]
	ds_read_b128 v[176:179], v149 offset:4352
	s_nop 6
	v_pk_mul_f32 v[158:159], v[98:99], v[158:159] op_sel_hi:[0,1]
	v_pk_mul_f32 v[156:157], v[98:99], v[156:157] op_sel_hi:[0,1]
	s_waitcnt lgkmcnt(0)
	s_nop 0
	v_mfma_f32_16x16x32_bf16 v[156:159], v[176:179], v[82:85], v[156:159]
	ds_read_b128 v[176:179], v149 offset:4416
	s_waitcnt lgkmcnt(0)
	v_mfma_f32_16x16x32_bf16 v[156:159], v[176:179], v[86:89], v[156:159]
	ds_read_b128 v[176:179], v149 offset:4480
	s_waitcnt lgkmcnt(0)
	v_mfma_f32_16x16x32_bf16 v[156:159], v[176:179], v[90:93], v[156:159]
	ds_read_b128 v[176:179], v149 offset:4544
	s_waitcnt lgkmcnt(0)
	v_mfma_f32_16x16x32_bf16 v[156:159], v[176:179], v[94:97], v[156:159]
	ds_read_b128 v[176:179], v148 offset:8768
	s_nop 6
	v_pk_mul_f32 v[112:113], v[100:101], v[158:159] op_sel_hi:[0,1]
	v_pk_mul_f32 v[156:157], v[100:101], v[156:157] op_sel_hi:[0,1]
	v_cvt_pk_bf16_f32 v156, v156, v157
	v_cvt_pk_bf16_f32 v157, v112, v113
	global_store_dwordx2 v[110:111], v[156:157], off offset:32
	ds_read_b128 v[156:159], v148 offset:8704
	s_waitcnt lgkmcnt(0)
	v_mfma_f32_16x16x32_bf16 v[156:159], v[156:159], v[78:81], 0
	v_mfma_f32_16x16x32_bf16 v[156:159], v[176:179], v[74:77], v[156:159]
	ds_read_b128 v[176:179], v148 offset:8832
	s_waitcnt lgkmcnt(0)
	v_mfma_f32_16x16x32_bf16 v[156:159], v[176:179], v[70:73], v[156:159]
	ds_read_b128 v[176:179], v148 offset:8896
	s_waitcnt lgkmcnt(0)
	v_mfma_f32_16x16x32_bf16 v[156:159], v[176:179], v[66:69], v[156:159]
	ds_read_b128 v[176:179], v149 offset:8704
	s_nop 6
	v_pk_mul_f32 v[158:159], v[98:99], v[158:159] op_sel_hi:[0,1]
	v_pk_mul_f32 v[156:157], v[98:99], v[156:157] op_sel_hi:[0,1]
	s_waitcnt lgkmcnt(0)
	s_nop 0
	v_mfma_f32_16x16x32_bf16 v[156:159], v[176:179], v[82:85], v[156:159]
	ds_read_b128 v[176:179], v149 offset:8768
	s_waitcnt lgkmcnt(0)
	v_mfma_f32_16x16x32_bf16 v[156:159], v[176:179], v[86:89], v[156:159]
	ds_read_b128 v[176:179], v149 offset:8832
	s_waitcnt lgkmcnt(0)
	v_mfma_f32_16x16x32_bf16 v[156:159], v[176:179], v[90:93], v[156:159]
	ds_read_b128 v[176:179], v149 offset:8896
	s_waitcnt lgkmcnt(0)
	v_mfma_f32_16x16x32_bf16 v[156:159], v[176:179], v[94:97], v[156:159]
	ds_read_b128 v[176:179], v148 offset:13120
	s_nop 6
	v_pk_mul_f32 v[112:113], v[100:101], v[158:159] op_sel_hi:[0,1]
	v_pk_mul_f32 v[156:157], v[100:101], v[156:157] op_sel_hi:[0,1]
	v_cvt_pk_bf16_f32 v156, v156, v157
	v_cvt_pk_bf16_f32 v157, v112, v113
	global_store_dwordx2 v[110:111], v[156:157], off offset:64
	ds_read_b128 v[156:159], v148 offset:13056
	s_waitcnt lgkmcnt(0)
	v_mfma_f32_16x16x32_bf16 v[156:159], v[156:159], v[78:81], 0
	v_mfma_f32_16x16x32_bf16 v[156:159], v[176:179], v[74:77], v[156:159]
	ds_read_b128 v[176:179], v148 offset:13184
	s_waitcnt lgkmcnt(0)
	v_mfma_f32_16x16x32_bf16 v[156:159], v[176:179], v[70:73], v[156:159]
	ds_read_b128 v[176:179], v148 offset:13248
	s_waitcnt lgkmcnt(0)
	v_mfma_f32_16x16x32_bf16 v[156:159], v[176:179], v[66:69], v[156:159]
	ds_read_b128 v[176:179], v149 offset:13056
	s_nop 6
	v_pk_mul_f32 v[158:159], v[98:99], v[158:159] op_sel_hi:[0,1]
	v_pk_mul_f32 v[156:157], v[98:99], v[156:157] op_sel_hi:[0,1]
	s_waitcnt lgkmcnt(0)
	s_nop 0
	v_mfma_f32_16x16x32_bf16 v[156:159], v[176:179], v[82:85], v[156:159]
	ds_read_b128 v[176:179], v149 offset:13120
	s_waitcnt lgkmcnt(0)
	v_mfma_f32_16x16x32_bf16 v[156:159], v[176:179], v[86:89], v[156:159]
	ds_read_b128 v[176:179], v149 offset:13184
	s_waitcnt lgkmcnt(0)
	v_mfma_f32_16x16x32_bf16 v[156:159], v[176:179], v[90:93], v[156:159]
	ds_read_b128 v[176:179], v149 offset:13248
	s_waitcnt lgkmcnt(0)
	v_mfma_f32_16x16x32_bf16 v[156:159], v[176:179], v[94:97], v[156:159]
	ds_read_b128 v[176:179], v148 offset:17472
	s_nop 6
	v_pk_mul_f32 v[112:113], v[100:101], v[158:159] op_sel_hi:[0,1]
	v_pk_mul_f32 v[156:157], v[100:101], v[156:157] op_sel_hi:[0,1]
	v_cvt_pk_bf16_f32 v156, v156, v157
	v_cvt_pk_bf16_f32 v157, v112, v113
	global_store_dwordx2 v[110:111], v[156:157], off offset:96
	ds_read_b128 v[156:159], v148 offset:17408
	s_waitcnt lgkmcnt(0)
	v_mfma_f32_16x16x32_bf16 v[156:159], v[156:159], v[78:81], 0
	v_mfma_f32_16x16x32_bf16 v[156:159], v[176:179], v[74:77], v[156:159]
	ds_read_b128 v[176:179], v148 offset:17536
	s_waitcnt lgkmcnt(0)
	v_mfma_f32_16x16x32_bf16 v[156:159], v[176:179], v[70:73], v[156:159]
	ds_read_b128 v[176:179], v148 offset:17600
	s_waitcnt lgkmcnt(0)
	v_mfma_f32_16x16x32_bf16 v[156:159], v[176:179], v[66:69], v[156:159]
	ds_read_b128 v[176:179], v149 offset:17408
	s_nop 6
	v_pk_mul_f32 v[158:159], v[98:99], v[158:159] op_sel_hi:[0,1]
	v_pk_mul_f32 v[156:157], v[98:99], v[156:157] op_sel_hi:[0,1]
	s_waitcnt lgkmcnt(0)
	s_nop 0
	v_mfma_f32_16x16x32_bf16 v[156:159], v[176:179], v[82:85], v[156:159]
	ds_read_b128 v[176:179], v149 offset:17472
	s_waitcnt lgkmcnt(0)
	v_mfma_f32_16x16x32_bf16 v[156:159], v[176:179], v[86:89], v[156:159]
	ds_read_b128 v[176:179], v149 offset:17536
	s_waitcnt lgkmcnt(0)
	v_mfma_f32_16x16x32_bf16 v[156:159], v[176:179], v[90:93], v[156:159]
	ds_read_b128 v[176:179], v149 offset:17600
	s_waitcnt lgkmcnt(0)
	v_mfma_f32_16x16x32_bf16 v[156:159], v[176:179], v[94:97], v[156:159]
	ds_read_b128 v[176:179], v148 offset:21824
	s_nop 6
	v_pk_mul_f32 v[112:113], v[100:101], v[158:159] op_sel_hi:[0,1]
	v_pk_mul_f32 v[156:157], v[100:101], v[156:157] op_sel_hi:[0,1]
	v_cvt_pk_bf16_f32 v156, v156, v157
	v_cvt_pk_bf16_f32 v157, v112, v113
	global_store_dwordx2 v[110:111], v[156:157], off offset:128
	ds_read_b128 v[156:159], v148 offset:21760
	s_waitcnt lgkmcnt(0)
	v_mfma_f32_16x16x32_bf16 v[156:159], v[156:159], v[78:81], 0
	v_mfma_f32_16x16x32_bf16 v[156:159], v[176:179], v[74:77], v[156:159]
	ds_read_b128 v[176:179], v148 offset:21888
	s_waitcnt lgkmcnt(0)
	v_mfma_f32_16x16x32_bf16 v[156:159], v[176:179], v[70:73], v[156:159]
	ds_read_b128 v[176:179], v148 offset:21952
	s_waitcnt lgkmcnt(0)
	v_mfma_f32_16x16x32_bf16 v[156:159], v[176:179], v[66:69], v[156:159]
	ds_read_b128 v[176:179], v149 offset:21760
	s_nop 6
	v_pk_mul_f32 v[158:159], v[98:99], v[158:159] op_sel_hi:[0,1]
	v_pk_mul_f32 v[156:157], v[98:99], v[156:157] op_sel_hi:[0,1]
	s_waitcnt lgkmcnt(0)
	s_nop 0
	v_mfma_f32_16x16x32_bf16 v[156:159], v[176:179], v[82:85], v[156:159]
	ds_read_b128 v[176:179], v149 offset:21824
	s_waitcnt lgkmcnt(0)
	v_mfma_f32_16x16x32_bf16 v[156:159], v[176:179], v[86:89], v[156:159]
	ds_read_b128 v[176:179], v149 offset:21888
	s_waitcnt lgkmcnt(0)
	v_mfma_f32_16x16x32_bf16 v[156:159], v[176:179], v[90:93], v[156:159]
	ds_read_b128 v[176:179], v149 offset:21952
	s_waitcnt lgkmcnt(0)
	v_mfma_f32_16x16x32_bf16 v[156:159], v[176:179], v[94:97], v[156:159]
	ds_read_b128 v[176:179], v148 offset:26176
	s_nop 6
	v_pk_mul_f32 v[112:113], v[100:101], v[158:159] op_sel_hi:[0,1]
	v_pk_mul_f32 v[156:157], v[100:101], v[156:157] op_sel_hi:[0,1]
	v_cvt_pk_bf16_f32 v156, v156, v157
	v_cvt_pk_bf16_f32 v157, v112, v113
	global_store_dwordx2 v[110:111], v[156:157], off offset:160
	ds_read_b128 v[156:159], v148 offset:26112
	s_waitcnt lgkmcnt(0)
	v_mfma_f32_16x16x32_bf16 v[156:159], v[156:159], v[78:81], 0
	v_mfma_f32_16x16x32_bf16 v[156:159], v[176:179], v[74:77], v[156:159]
	ds_read_b128 v[176:179], v148 offset:26240
	s_waitcnt lgkmcnt(0)
	v_mfma_f32_16x16x32_bf16 v[156:159], v[176:179], v[70:73], v[156:159]
	ds_read_b128 v[176:179], v148 offset:26304
	s_waitcnt lgkmcnt(0)
	v_mfma_f32_16x16x32_bf16 v[156:159], v[176:179], v[66:69], v[156:159]
	ds_read_b128 v[176:179], v149 offset:26112
	s_nop 6
	v_pk_mul_f32 v[158:159], v[98:99], v[158:159] op_sel_hi:[0,1]
	v_pk_mul_f32 v[156:157], v[98:99], v[156:157] op_sel_hi:[0,1]
	s_waitcnt lgkmcnt(0)
	s_nop 0
	v_mfma_f32_16x16x32_bf16 v[156:159], v[176:179], v[82:85], v[156:159]
	ds_read_b128 v[176:179], v149 offset:26176
	s_waitcnt lgkmcnt(0)
	v_mfma_f32_16x16x32_bf16 v[156:159], v[176:179], v[86:89], v[156:159]
	ds_read_b128 v[176:179], v149 offset:26240
	s_waitcnt lgkmcnt(0)
	v_mfma_f32_16x16x32_bf16 v[156:159], v[176:179], v[90:93], v[156:159]
	ds_read_b128 v[176:179], v149 offset:26304
	s_waitcnt lgkmcnt(0)
	v_mfma_f32_16x16x32_bf16 v[156:159], v[176:179], v[94:97], v[156:159]
	s_nop 7
	v_pk_mul_f32 v[112:113], v[100:101], v[158:159] op_sel_hi:[0,1]
	v_pk_mul_f32 v[156:157], v[100:101], v[156:157] op_sel_hi:[0,1]
	v_cvt_pk_bf16_f32 v156, v156, v157
	v_cvt_pk_bf16_f32 v157, v112, v113
	global_store_dwordx2 v[110:111], v[156:157], off offset:192
	ds_read_b128 v[156:159], v148 offset:30464
	s_waitcnt lgkmcnt(0)
	v_mfma_f32_16x16x32_bf16 v[78:81], v[156:159], v[78:81], 0
	ds_read_b128 v[156:159], v148 offset:30528
	s_waitcnt lgkmcnt(0)
	v_mfma_f32_16x16x32_bf16 v[74:77], v[156:159], v[74:77], v[78:81]
	s_nop 4
	ds_read_b128 v[78:81], v148 offset:30592
	s_waitcnt lgkmcnt(0)
	v_mfma_f32_16x16x32_bf16 v[70:73], v[78:81], v[70:73], v[74:77]
	s_nop 2
	ds_read_b128 v[74:77], v148 offset:30656
	s_waitcnt lgkmcnt(0)
	v_mfma_f32_16x16x32_bf16 v[66:69], v[74:77], v[66:69], v[70:73]
	s_nop 2
	ds_read_b128 v[70:73], v149 offset:30464
	s_nop 3
	v_pk_mul_f32 v[68:69], v[98:99], v[68:69] op_sel_hi:[0,1]
	v_pk_mul_f32 v[66:67], v[98:99], v[66:67] op_sel_hi:[0,1]
	s_waitcnt lgkmcnt(0)
	s_nop 0
	v_mfma_f32_16x16x32_bf16 v[66:69], v[70:73], v[82:85], v[66:69]
	ds_read_b128 v[70:73], v149 offset:30528
	s_waitcnt lgkmcnt(0)
	v_mfma_f32_16x16x32_bf16 v[66:69], v[70:73], v[86:89], v[66:69]
	ds_read_b128 v[70:73], v149 offset:30592
	s_waitcnt lgkmcnt(0)
	v_mfma_f32_16x16x32_bf16 v[66:69], v[70:73], v[90:93], v[66:69]
	ds_read_b128 v[70:73], v149 offset:30656
	s_waitcnt lgkmcnt(0)
	v_mfma_f32_16x16x32_bf16 v[66:69], v[70:73], v[94:97], v[66:69]
	s_nop 7
	v_pk_mul_f32 v[68:69], v[100:101], v[68:69] op_sel_hi:[0,1]
	v_pk_mul_f32 v[66:67], v[100:101], v[66:67] op_sel_hi:[0,1]
	v_cvt_pk_bf16_f32 v66, v66, v67
	v_cvt_pk_bf16_f32 v67, v68, v69
	global_store_dwordx2 v[110:111], v[66:67], off offset:224
	v_sub_f32_e32 v66, v154, v152
	v_mul_f32_e32 v82, 0x3fb8aa3b, v66
	ds_read_b128 v[78:81], v150
	ds_read_b128 v[74:77], v150 offset:64
	ds_read_b128 v[70:73], v150 offset:128
	ds_read_b128 v[66:69], v150 offset:192
	v_exp_f32_e32 v82, v82
	ds_read_b128 v[84:87], v151 offset:34816
	v_pk_mul_f32 v[4:5], v[4:5], v[82:83] op_sel_hi:[1,0]
	v_pk_mul_f32 v[2:3], v[2:3], v[82:83] op_sel_hi:[1,0]
	v_pk_mul_f32 v[8:9], v[8:9], v[82:83] op_sel_hi:[1,0]
	v_pk_mul_f32 v[6:7], v[6:7], v[82:83] op_sel_hi:[1,0]
	s_waitcnt lgkmcnt(0)
	v_mfma_f32_16x16x32_bf16 v[2:5], v[78:81], v[84:87], v[2:5]
	ds_read_b128 v[84:87], v151 offset:34880
	v_pk_mul_f32 v[12:13], v[12:13], v[82:83] op_sel_hi:[1,0]
	v_pk_mul_f32 v[10:11], v[10:11], v[82:83] op_sel_hi:[1,0]
	s_waitcnt lgkmcnt(0)
	v_mfma_f32_16x16x32_bf16 v[2:5], v[74:77], v[84:87], v[2:5]
	ds_read_b128 v[84:87], v151 offset:34944
	v_pk_mul_f32 v[16:17], v[16:17], v[82:83] op_sel_hi:[1,0]
	v_pk_mul_f32 v[14:15], v[14:15], v[82:83] op_sel_hi:[1,0]
	s_waitcnt lgkmcnt(0)
	v_mfma_f32_16x16x32_bf16 v[2:5], v[70:73], v[84:87], v[2:5]
	ds_read_b128 v[84:87], v151 offset:35008
	v_pk_mul_f32 v[20:21], v[20:21], v[82:83] op_sel_hi:[1,0]
	v_pk_mul_f32 v[18:19], v[18:19], v[82:83] op_sel_hi:[1,0]
	s_waitcnt lgkmcnt(0)
	v_mfma_f32_16x16x32_bf16 v[2:5], v[66:69], v[84:87], v[2:5]
	ds_read_b128 v[84:87], v151 offset:39168
	v_pk_mul_f32 v[24:25], v[24:25], v[82:83] op_sel_hi:[1,0]
	v_pk_mul_f32 v[22:23], v[22:23], v[82:83] op_sel_hi:[1,0]
	s_waitcnt lgkmcnt(0)
	v_mfma_f32_16x16x32_bf16 v[6:9], v[78:81], v[84:87], v[6:9]
	ds_read_b128 v[84:87], v151 offset:39232
	v_pk_mul_f32 v[28:29], v[28:29], v[82:83] op_sel_hi:[1,0]
	v_pk_mul_f32 v[26:27], v[26:27], v[82:83] op_sel_hi:[1,0]
	s_waitcnt lgkmcnt(0)
	v_mfma_f32_16x16x32_bf16 v[6:9], v[74:77], v[84:87], v[6:9]
	ds_read_b128 v[84:87], v151 offset:39296
	v_pk_mul_f32 v[32:33], v[32:33], v[82:83] op_sel_hi:[1,0]
	v_pk_mul_f32 v[30:31], v[30:31], v[82:83] op_sel_hi:[1,0]
	s_waitcnt lgkmcnt(0)
	v_mfma_f32_16x16x32_bf16 v[6:9], v[70:73], v[84:87], v[6:9]
	ds_read_b128 v[84:87], v151 offset:39360
	s_waitcnt lgkmcnt(0)
	v_mfma_f32_16x16x32_bf16 v[6:9], v[66:69], v[84:87], v[6:9]
	ds_read_b128 v[84:87], v151 offset:43520
	s_waitcnt lgkmcnt(0)
	v_mfma_f32_16x16x32_bf16 v[10:13], v[78:81], v[84:87], v[10:13]
	ds_read_b128 v[84:87], v151 offset:43584
	s_waitcnt lgkmcnt(0)
	v_mfma_f32_16x16x32_bf16 v[10:13], v[74:77], v[84:87], v[10:13]
	ds_read_b128 v[84:87], v151 offset:43648
	s_waitcnt lgkmcnt(0)
	v_mfma_f32_16x16x32_bf16 v[10:13], v[70:73], v[84:87], v[10:13]
	ds_read_b128 v[84:87], v151 offset:43712
	s_waitcnt lgkmcnt(0)
	v_mfma_f32_16x16x32_bf16 v[10:13], v[66:69], v[84:87], v[10:13]
	ds_read_b128 v[84:87], v151 offset:47872
	s_waitcnt lgkmcnt(0)
	v_mfma_f32_16x16x32_bf16 v[14:17], v[78:81], v[84:87], v[14:17]
	ds_read_b128 v[84:87], v151 offset:47936
	s_waitcnt lgkmcnt(0)
	v_mfma_f32_16x16x32_bf16 v[14:17], v[74:77], v[84:87], v[14:17]
	ds_read_b128 v[84:87], v151 offset:48000
	s_waitcnt lgkmcnt(0)
	v_mfma_f32_16x16x32_bf16 v[14:17], v[70:73], v[84:87], v[14:17]
	ds_read_b128 v[84:87], v151 offset:48064
	s_waitcnt lgkmcnt(0)
	v_mfma_f32_16x16x32_bf16 v[14:17], v[66:69], v[84:87], v[14:17]
	ds_read_b128 v[84:87], v151 offset:52224
	s_waitcnt lgkmcnt(0)
	v_mfma_f32_16x16x32_bf16 v[18:21], v[78:81], v[84:87], v[18:21]
	ds_read_b128 v[84:87], v151 offset:52288
	s_waitcnt lgkmcnt(0)
	v_mfma_f32_16x16x32_bf16 v[18:21], v[74:77], v[84:87], v[18:21]
	ds_read_b128 v[84:87], v151 offset:52352
	s_waitcnt lgkmcnt(0)
	v_mfma_f32_16x16x32_bf16 v[18:21], v[70:73], v[84:87], v[18:21]
	ds_read_b128 v[84:87], v151 offset:52416
	s_waitcnt lgkmcnt(0)
	v_mfma_f32_16x16x32_bf16 v[18:21], v[66:69], v[84:87], v[18:21]
	ds_read_b128 v[84:87], v151 offset:56576
	s_waitcnt lgkmcnt(0)
	v_mfma_f32_16x16x32_bf16 v[22:25], v[78:81], v[84:87], v[22:25]
	ds_read_b128 v[84:87], v151 offset:56640
	s_waitcnt lgkmcnt(0)
	v_mfma_f32_16x16x32_bf16 v[22:25], v[74:77], v[84:87], v[22:25]
	ds_read_b128 v[84:87], v151 offset:56704
	s_waitcnt lgkmcnt(0)
	v_mfma_f32_16x16x32_bf16 v[22:25], v[70:73], v[84:87], v[22:25]
	ds_read_b128 v[84:87], v151 offset:56768
	s_waitcnt lgkmcnt(0)
	v_mfma_f32_16x16x32_bf16 v[22:25], v[66:69], v[84:87], v[22:25]
	ds_read_b128 v[84:87], v151 offset:60928
	s_waitcnt lgkmcnt(0)
	v_mfma_f32_16x16x32_bf16 v[26:29], v[78:81], v[84:87], v[26:29]
	ds_read_b128 v[84:87], v151 offset:60992
	s_waitcnt lgkmcnt(0)
	v_mfma_f32_16x16x32_bf16 v[26:29], v[74:77], v[84:87], v[26:29]
	ds_read_b128 v[84:87], v151 offset:61056
	s_waitcnt lgkmcnt(0)
	v_mfma_f32_16x16x32_bf16 v[26:29], v[70:73], v[84:87], v[26:29]
	ds_read_b128 v[84:87], v151 offset:61120
	s_waitcnt lgkmcnt(0)
	v_mfma_f32_16x16x32_bf16 v[26:29], v[66:69], v[84:87], v[26:29]
	ds_read_b128 v[84:87], v151 offset:65280
	s_waitcnt lgkmcnt(0)
	v_mfma_f32_16x16x32_bf16 v[30:33], v[78:81], v[84:87], v[30:33]
	ds_read_b128 v[78:81], v151 offset:65344
	s_waitcnt lgkmcnt(0)
	v_mfma_f32_16x16x32_bf16 v[30:33], v[74:77], v[78:81], v[30:33]
	ds_read_b128 v[74:77], v151 offset:65408
	s_waitcnt lgkmcnt(0)
	v_mfma_f32_16x16x32_bf16 v[30:33], v[70:73], v[74:77], v[30:33]
	ds_read_b128 v[70:73], v151 offset:65472
	s_waitcnt lgkmcnt(0)
	v_mfma_f32_16x16x32_bf16 v[30:33], v[66:69], v[70:73], v[30:33]
	v_lshrrev_b32_e32 v66, 6, v163
	v_and_b32_e32 v67, 15, v163
	v_lshl_add_u32 v66, v66, 4, v67
	v_bfe_u32 v67, v163, 4, 2
	v_mul_u32_u24_e32 v68, 0x110, v66
	v_lshl_add_u32 v67, v67, 4, v68
	v_lshlrev_b32_e32 v66, 2, v66
	v_add_u32_e32 v66, 0x22600, v66
	v_mov_b32_e32 v76, 0x3f803f80
	v_mov_b32_e32 v77, 0x3f803f80
	v_mov_b32_e32 v78, 0x3f803f80
	v_mov_b32_e32 v79, 0x3f803f80
	ds_read_b128 v[68:71], v67 offset:34816
	ds_read_b128 v[72:75], v67 offset:34880
	s_waitcnt lgkmcnt(1)
	v_mfma_f32_16x16x32_bf16 v[84:87], v[76:79], v[68:71], 0
	ds_read_b128 v[68:71], v67 offset:34944
	s_waitcnt lgkmcnt(1)
	v_mfma_f32_16x16x32_bf16 v[84:87], v[76:79], v[72:75], v[84:87]
	ds_read_b128 v[72:75], v67 offset:35008
	ds_read_b32 v67, v66
	s_waitcnt lgkmcnt(2)
	v_mfma_f32_16x16x32_bf16 v[84:87], v[76:79], v[68:71], v[84:87]
	s_waitcnt lgkmcnt(1)
	v_mfma_f32_16x16x32_bf16 v[84:87], v[76:79], v[72:75], v[84:87]
	s_waitcnt lgkmcnt(0)
	s_nop 7
	s_nop 1
	v_fmac_f32_e32 v84, v82, v67
.LBB0_695:
	s_barrier
	s_mov_b64 s[90:91], exec
	s_mov_b64 exec, 0xffff
	ds_write_b32 v66, v84
	s_branch .LBB0_680
